# attention phase: per-cluster s_setprio flips deleted, one static s_setprio 1 for waves 4-7 for the whole phase (reset at phase end)
# baseline (speedup 1.0000x reference)
; DI void attn_item(LAS unsigned char* lds, int bh, int qb, const bf16_t* QH, const bf16_t* KN, const bf16_t* KPE, const bf16_t* VT, const bf16_t* P, bf16_t* MIX) {
;     const int tid = threadIdx.x, lane = tid & 63, wid = __builtin_amdgcn_readfirstlane(tid >> 6);
;     const int rg = wid & 3, kh = wid >> 2, r = lane & 31, h2 = lane >> 5;
;     const int b = bh >> 3, h = bh & 7;
;     const int q0 = qb * 128;
;     const int ntile = 2 * (qb + 1);
;     const bf16_t* ksrc[3]; int kdst[3];
; #pragma unroll
;     for (int j = 0; j < 3; ++j) { const int id = tid + 512 * j, key = id / 24, ch = id - key * 24;
;         ksrc[j] = ch < 16 ? KN + ((size_t)bh * SEQ + key) * 128 + ch * 8 : KPE + ((size_t)b * SEQ + key) * 64 + (ch - 16) * 8;
;         kdst[j] = key * KROW + ch * 16; }
;     const bf16_t* vsrc[2]; int vdst[2];
; #pragma unroll
;     for (int j = 0; j < 2; ++j) { const int id = tid + 512 * j, key = id >> 4, ch = id & 15;
;         vsrc[j] = VT + ((size_t)bh * SEQ + key) * 128 + ch * 8; vdst[j] = key * VROW + ch * 16; }
;     const size_t kstep_n = (size_t)64 * 128, kstep_p = (size_t)64 * 64;
;     u32x4 kreg[3], vreg[2];
.LBB0_590:
	s_cmp_lt_i32 s84, 5
	s_cselect_b64 s[4:5], -1, 0
	s_and_b64 s[14:15], s[4:5], s[0:1]
	s_cmpk_lt_i32 s52, 0x100
	s_cselect_b64 s[0:1], -1, 0
	s_and_b64 s[0:1], s[14:15], s[0:1]
	s_andn2_b64 vcc, exec, s[0:1]
	s_cbranch_vccnz .LBB0_625
	v_readlane_b32 s100, v254, 3
	s_nop 0
	s_cmp_lt_u32 s100, 4
	s_cbranch_scc1 .Lprio4_done
	s_setprio 1
.Lprio4_done:
	s_add_u32 s0, s82, 0xd580000
	s_addc_u32 s1, s83, 0
	v_mul_u32_u24_e32 v0, 0xaab, v253
	s_add_u32 s10, s82, 0xf580000
	v_lshrrev_b32_e32 v6, 16, v0
	s_movk_i32 s8, 0xffe8
	s_addc_u32 s11, s83, 0
	v_mad_i32_i24 v4, v6, s8, v253
	v_lshlrev_b32_e32 v148, 7, v6
	v_mov_b32_e32 v149, 0
	v_lshlrev_b32_e32 v0, 3, v4
	v_lshl_add_u64 v[2:3], s[10:11], 0, v[148:149]
	s_waitcnt lgkmcnt(0)
	v_mov_b32_e32 v1, v149
	v_lshlrev_b32_e32 v148, 8, v6
	v_lshl_add_u64 v[150:151], v[0:1], 1, v[2:3]
	v_lshl_add_u64 v[2:3], s[0:1], 0, v[148:149]
	v_ashrrev_i32_e32 v1, 31, v0
	s_waitcnt vmcnt(0)
	v_lshl_add_u64 v[152:153], v[0:1], 1, v[2:3]
	v_mul_u32_u24_e32 v0, 0x190, v6
	v_add_u32_e32 v7, 0x200, v253
	v_lshl_add_u32 v171, v4, 4, v0
	v_mul_u32_u24_e32 v0, 0xaab, v7
	v_lshrrev_b32_e32 v8, 16, v0
	v_cmp_gt_i32_e64 s[4:5], 16, v4
	v_mad_i32_i24 v4, v8, s8, v7
	v_lshlrev_b32_e32 v148, 7, v8
	v_lshlrev_b32_e32 v0, 3, v4
	v_lshl_add_u64 v[2:3], s[10:11], 0, v[148:149]
	v_mov_b32_e32 v1, v149
	v_lshlrev_b32_e32 v148, 8, v8
	v_lshl_add_u64 v[154:155], v[0:1], 1, v[2:3]
	v_lshl_add_u64 v[2:3], s[0:1], 0, v[148:149]
	v_ashrrev_i32_e32 v1, 31, v0
	v_lshl_add_u64 v[156:157], v[0:1], 1, v[2:3]
	v_mul_u32_u24_e32 v0, 0x190, v8
	v_or_b32_e32 v9, 0x400, v253
	v_lshl_add_u32 v173, v4, 4, v0
	v_mul_u32_u24_e32 v0, 0xaab, v9
	v_lshrrev_b32_e32 v10, 16, v0
	v_cmp_gt_i32_e64 s[6:7], 16, v4
	v_mad_i32_i24 v4, v10, s8, v9
	v_lshlrev_b32_e32 v148, 7, v10
	v_lshlrev_b32_e32 v0, 3, v4
	v_lshl_add_u64 v[2:3], s[10:11], 0, v[148:149]
	v_mov_b32_e32 v1, v149
	v_lshlrev_b32_e32 v148, 8, v10
	v_lshl_add_u64 v[158:159], v[0:1], 1, v[2:3]
	v_lshl_add_u64 v[2:3], s[0:1], 0, v[148:149]
	v_ashrrev_i32_e32 v1, 31, v0
	v_lshl_add_u64 v[160:161], v[0:1], 1, v[2:3]
	v_mul_u32_u24_e32 v0, 0x190, v10
	v_lshl_add_u32 v220, v4, 4, v0
	v_and_b32_e32 v0, 15, v253
	v_lshlrev_b32_e32 v148, 4, v0
	v_lshrrev_b32_e32 v11, 5, v252
	v_lshl_add_u64 v[0:1], s[82:83], 0, v[148:149]
	s_mov_b64 s[0:1], 0xe580000
	v_lshlrev_b32_e32 v164, 4, v11
	v_mov_b32_e32 v165, v149
	v_cmp_gt_i32_e64 s[8:9], 16, v4
	v_lshl_add_u64 v[162:163], v[0:1], 0, s[0:1]
	v_lshl_add_u64 v[4:5], s[82:83], 0, v[164:165]
	s_mov_b64 s[0:1], 0xbd80000
	v_lshl_add_u64 v[166:167], v[4:5], 0, s[0:1]
	v_mul_lo_u16_e32 v4, 24, v6
	v_mul_lo_u16_e32 v6, 24, v8
	v_lshrrev_b32_e32 v3, 4, v7
	v_sub_u16_e32 v6, v7, v6
	v_mul_lo_u16_e32 v7, 24, v10
	v_sub_u16_e32 v4, v253, v4
	v_sub_u16_e32 v7, v9, v7
	v_mov_b32_e32 v5, 0x1000
	v_mov_b32_e32 v12, 0x2000
	v_cmp_gt_u16_e32 vcc, 16, v4
	v_cmp_gt_u16_e64 s[0:1], 16, v6
	v_cmp_gt_u16_e64 s[10:11], 16, v7
	v_lshrrev_b32_e32 v1, 4, v253
	v_cndmask_b32_e32 v4, v5, v12, vcc
	v_cndmask_b32_e64 v6, v5, v12, s[0:1]
	v_cndmask_b32_e64 v8, v5, v12, s[10:11]
	v_mbcnt_lo_u32_b32 v5, -1, 0
	v_cndmask_b32_e64 v172, 12, 13, s[10:11]
	s_add_i32 s10, 0, 0x11000
	v_mbcnt_hi_u32_b32 v5, -1, v5
	v_lshlrev_b32_e32 v223, 2, v11
	v_lshl_add_u32 v227, v11, 3, s10
	v_lshl_or_b32 v10, v1, 8, v148
	v_mov_b32_e32 v11, v149
	v_and_b32_e32 v9, 64, v5
	v_cndmask_b32_e64 v170, 12, 13, s[0:1]
	v_lshl_add_u64 v[10:11], s[82:83], 0, v[10:11]
	s_mov_b64 s[0:1], 0xe588000
	v_xor_b32_e32 v7, 32, v5
	v_add_u32_e32 v9, 64, v9
	v_lshl_add_u64 v[174:175], v[10:11], 0, s[0:1]
	v_lshl_or_b32 v10, v3, 8, v148
	v_mov_b32_e32 v11, v149
	v_cmp_lt_i32_e64 s[12:13], v7, v9
	v_lshl_add_u64 v[10:11], s[82:83], 0, v[10:11]
	v_lshl_add_u64 v[176:177], v[10:11], 0, s[0:1]
	v_cndmask_b32_e64 v5, v5, v7, s[12:13]
	v_lshl_or_b32 v10, v1, 12, v148
	v_mov_b32_e32 v11, v149
	v_lshlrev_b32_e32 v165, 2, v5
	v_lshrrev_b32_e32 v5, 2, v253
	v_lshl_add_u64 v[10:11], s[80:81], 0, v[10:11]
	s_mov_b64 s[0:1], 0x800
	v_and_or_b32 v224, v5, 3, v223
	v_lshlrev_b32_e32 v5, 1, v253
	v_lshl_add_u64 v[178:179], v[10:11], 0, s[0:1]
	s_movk_i32 s0, 0x2880
	v_and_b32_e32 v225, 32, v5
	v_lshlrev_b32_e32 v5, 3, v253
	v_mad_u64_u32 v[10:11], s[0:1], v1, s0, v[148:149]
	s_movk_i32 s26, 0x140
	v_and_b32_e32 v226, 24, v5
	v_lshlrev_b32_e32 v5, 4, v253
	v_lshl_add_u64 v[10:11], s[82:83], 0, v[10:11]
	s_mov_b64 s[0:1], 0x6c82080
	v_lshlrev_b32_e32 v0, 7, v1
	v_mad_u32_u24 v221, v1, s26, v148
	v_lshlrev_b32_e32 v2, 7, v3
	v_and_b32_e32 v5, 0xf0, v5
	v_lshl_add_u64 v[180:181], v[10:11], 0, s[0:1]
	v_mul_u32_u24_e32 v1, 0x110, v1
	s_movk_i32 s0, 0xff00
	v_and_b32_e32 v169, 31, v253
	s_movk_i32 s3, 0x190
	v_mad_u32_u24 v222, v3, s26, v148
	v_cndmask_b32_e64 v168, 12, 13, vcc
	s_movk_i32 s27, 0x110
	v_add3_u32 v228, v1, v5, s10
	s_mov_b32 s1, -1
	v_lshlrev_b32_e32 v148, 1, v0
	v_lshlrev_b32_e32 v182, 1, v2
	s_movk_i32 s28, 0x180
	v_lshlrev_b32_e32 v184, 1, v4
	v_lshlrev_b32_e32 v186, 1, v6
	v_lshlrev_b32_e32 v188, 1, v8
	s_mov_b64 s[10:11], 0x4000
	s_movk_i32 s29, 0x4000
	s_mov_b32 s30, 0xf149f2ca
	s_movk_i32 s31, 0x108
	s_mov_b64 s[12:13], 0x20000
	s_mov_b64 s[16:17], 0x51000
	v_mov_b32_e32 v229, 0x180
	v_mov_b32_e32 v230, 0xf149f2ca

; #define LAS __attribute__((address_space(3)))
; DI float fexp2(float x) { return __builtin_amdgcn_exp2f(x); }
; DI void attn_item(LAS unsigned char* lds, int bh, int qb, const bf16_t* QH, const bf16_t* KN, const bf16_t* KPE, const bf16_t* VT, const bf16_t* P, bf16_t* MIX) {
;     ...
;     for (int t = 0; t < ntile; ++t) {
;         __syncthreads();
;         if (t + 1 < ntile) { ATT_STORE((t + 1) & 1); if (t + 2 < ntile) ATT_LOAD(t + 2); }
;         LAS unsigned char* kb = lds + (t & 1) * ATT_STAGE; LAS unsigned char* vb = kb + KBUF_B;
;         f32x16 S;
; #pragma unroll
;         for (int i = 0; i < 16; ++i) S[i] = 0.f;
;         { const LAS unsigned char* kp = kb + (kh * 32 + r) * KROW + 16 * h2;
;           __builtin_amdgcn_s_setprio(1);
; #pragma unroll
;           for (int ks = 0; ks < 12; ++ks) { const bf16x8 a = *(const LAS bf16x8*)(kp + 32 * ks); S = __builtin_amdgcn_mfma_f32_32x32x16_bf16(a, Qf[ks], S, 0, 0, 0); }
;           __builtin_amdgcn_sched_group_barrier(0x100, 4, 0);
; #pragma unroll
;           for (int i = 0; i < 8; ++i) { __builtin_amdgcn_sched_group_barrier(0x008, 1, 0); __builtin_amdgcn_sched_group_barrier(0x100, 1, 0); }
;           __builtin_amdgcn_sched_group_barrier(0x008, 4, 0);
;           __builtin_amdgcn_s_setprio(0); }
;         const bool diag = (t >= 2 * qb);
;         if (diag) {
;             const int key0 = t * 64 + kh * 32 + 4 * h2;
; #pragma unroll
;             for (int i = 0; i < 16; ++i) { const int key = key0 + (i & 3) + 8 * (i >> 2); if (key > qpos) S[i] = NEG; }
;         }
;         float mx = S[0];
; #pragma unroll
;         for (int i = 1; i < 16; ++i) mx = fmaxf(mx, S[i]);
;         mx = fmaxf(mx, __shfl_xor(mx, 32));
;         if (__any(mx > mrow + 8.f)) {
;             const float mnew = fmaxf(mrow, mx);
;             const float alpha = fexp2(mrow - mnew);
;             mrow = mnew; lrow *= alpha;
; #pragma unroll
;             for (int d = 0; d < 4; ++d)
; #pragma unroll
;                 for (int i = 0; i < 16; ++i) O[d][i] *= alpha;
;         }
;         float ps = 0.f;
; #pragma unroll
;         for (int i = 0; i < 16; ++i) { float p = fexp2(S[i] - mrow); if (diag && S[i] == NEG) p = 0.f; S[i] = p; ps += p; }
.LBB0_593:
	v_sub_f32_e32 v64, v64, v214
	v_exp_f32_e32 v64, v64
	v_sub_f32_e32 v65, v65, v214
	v_exp_f32_e32 v65, v65
	v_sub_f32_e32 v66, v66, v214
	v_exp_f32_e32 v66, v66
	v_sub_f32_e32 v67, v67, v214
	v_exp_f32_e32 v67, v67
	v_sub_f32_e32 v68, v68, v214
	v_add_f32_e32 v235, 0, v64
	v_exp_f32_e32 v68, v68
	v_sub_f32_e32 v69, v69, v214
	v_add_f32_e32 v235, v65, v235
	v_exp_f32_e32 v69, v69
	v_sub_f32_e32 v70, v70, v214
	v_add_f32_e32 v235, v66, v235
	v_exp_f32_e32 v70, v70
	v_sub_f32_e32 v71, v71, v214
	v_add_f32_e32 v235, v67, v235
	v_exp_f32_e32 v71, v71
	v_sub_f32_e32 v72, v72, v214
	v_add_f32_e32 v235, v68, v235
	v_exp_f32_e32 v72, v72
	v_sub_f32_e32 v73, v73, v214
	v_add_f32_e32 v235, v69, v235
	v_exp_f32_e32 v73, v73
	v_sub_f32_e32 v74, v74, v214
	v_add_f32_e32 v235, v70, v235
	v_exp_f32_e32 v74, v74
	v_sub_f32_e32 v75, v75, v214
	v_add_f32_e32 v235, v71, v235
	v_exp_f32_e32 v75, v75
	v_sub_f32_e32 v76, v76, v214
	v_add_f32_e32 v235, v72, v235
	v_exp_f32_e32 v76, v76
	v_sub_f32_e32 v77, v77, v214
	v_add_f32_e32 v235, v73, v235
	v_exp_f32_e32 v77, v77
	v_sub_f32_e32 v78, v78, v214
	v_add_f32_e32 v235, v74, v235
	v_exp_f32_e32 v78, v78
	v_sub_f32_e32 v79, v79, v214
	v_add_f32_e32 v235, v75, v235
	v_exp_f32_e32 v79, v79
	v_add_f32_e32 v235, v76, v235
	v_add_f32_e32 v235, v77, v235
	v_add_f32_e32 v235, v78, v235
	v_add_f32_e32 v235, v79, v235
	v_cvt_pk_bf16_f32 v64, v64, v65
	v_cvt_pk_bf16_f32 v65, v66, v67
	v_cvt_pk_bf16_f32 v66, v68, v69
	v_cvt_pk_bf16_f32 v67, v70, v71
	v_cvt_pk_bf16_f32 v68, v72, v73
	v_cvt_pk_bf16_f32 v69, v74, v75
	v_cvt_pk_bf16_f32 v70, v76, v77
	v_cvt_pk_bf16_f32 v71, v78, v79
	s_nop 0
	v_add_u32_e32 v72, s44, v215
	v_add3_u32 v236, v72, v225, v226
	ds_read_b64_tr_b16 v[72:73], v236 offset:25600
	ds_read_b64_tr_b16 v[74:75], v236 offset:28160
	ds_read_b64_tr_b16 v[76:77], v236 offset:30720
	v_add_f32_e32 v234, v234, v235
	s_waitcnt lgkmcnt(1)
	v_mfma_f32_32x32x16_bf16 v[48:63], v[72:75], v[64:67], v[48:63]
	ds_read_b64_tr_b16 v[78:79], v236 offset:33280
	ds_read_b64_tr_b16 v[72:73], v236 offset:25664
	ds_read_b64_tr_b16 v[74:75], v236 offset:28224
	s_waitcnt lgkmcnt(2)
	v_mfma_f32_32x32x16_bf16 v[48:63], v[76:79], v[68:71], v[48:63]
	s_waitcnt lgkmcnt(0)
	v_mfma_f32_32x32x16_bf16 v[32:47], v[72:75], v[64:67], v[32:47]
	ds_read_b64_tr_b16 v[72:73], v236 offset:30784
	ds_read_b64_tr_b16 v[74:75], v236 offset:33344
	s_waitcnt lgkmcnt(0)
	v_mfma_f32_32x32x16_bf16 v[32:47], v[72:75], v[68:71], v[32:47]
	ds_read_b64_tr_b16 v[72:73], v236 offset:25728
	ds_read_b64_tr_b16 v[74:75], v236 offset:28288
	s_waitcnt lgkmcnt(0)
	v_mfma_f32_32x32x16_bf16 v[16:31], v[72:75], v[64:67], v[16:31]
	ds_read_b64_tr_b16 v[72:73], v236 offset:30848
	ds_read_b64_tr_b16 v[74:75], v236 offset:33408
	s_waitcnt lgkmcnt(0)
	v_mfma_f32_32x32x16_bf16 v[16:31], v[72:75], v[68:71], v[16:31]
	ds_read_b64_tr_b16 v[72:73], v236 offset:25792
	ds_read_b64_tr_b16 v[74:75], v236 offset:28352
	s_waitcnt lgkmcnt(0)
	v_mfma_f32_32x32x16_bf16 v[0:15], v[72:75], v[64:67], v[0:15]
	ds_read_b64_tr_b16 v[64:65], v236 offset:30912
	ds_read_b64_tr_b16 v[66:67], v236 offset:33472
	s_waitcnt lgkmcnt(0)
	v_mfma_f32_32x32x16_bf16 v[0:15], v[64:67], v[68:71], v[0:15]
	s_nop 0
	s_add_u32 s22, s22, 1
	s_addc_u32 s23, s23, 0
	s_add_i32 s44, s43, s22
	v_lshl_add_u64 v[218:219], v[218:219], 0, s[10:11]
	s_cmp_eq_u32 s44, 2
	v_lshl_add_u64 v[216:217], v[216:217], 0, s[10:11]
	s_cbranch_scc1 .LBB0_596
.LBB0_594:
	s_bitcmp1_b32 s22, 0
	s_cselect_b32 s40, 0, 0xb400
	s_cselect_b32 s44, 0xb400, 0
	s_add_i32 s40, s40, 0
	v_add_u32_e32 v64, s40, v171
	s_waitcnt lgkmcnt(0)
	s_barrier
	s_waitcnt vmcnt(4)
	ds_write_b128 v64, v[128:131]
	v_add_u32_e32 v64, s40, v173
	s_waitcnt vmcnt(3)
	ds_write_b128 v64, v[132:135]
	v_add_u32_e32 v64, s40, v220
	s_waitcnt vmcnt(0)
	ds_write_b128 v64, v[144:147]
	v_add_u32_e32 v64, s40, v221
	ds_write_b128 v64, v[136:139] offset:25600
	v_add_u32_e32 v64, s40, v222
	ds_write_b128 v64, v[140:143] offset:25600
	v_lshlrev_b64 v[64:65], v168, s[22:23]
	v_lshl_add_u64 v[64:65], v[64:65], 1, v[190:191]
	global_load_dwordx4 v[128:131], v[64:65], off
	v_lshlrev_b64 v[64:65], v170, s[22:23]
	v_lshl_add_u64 v[64:65], v[64:65], 1, v[192:193]
	global_load_dwordx4 v[132:135], v[64:65], off
	v_lshlrev_b64 v[64:65], v172, s[22:23]
	v_lshl_add_u64 v[64:65], v[64:65], 1, v[194:195]
	global_load_dwordx4 v[144:147], v[64:65], off
	global_load_dwordx4 v[136:139], v[218:219], off
	global_load_dwordx4 v[140:143], v[216:217], off
	s_add_i32 s44, s44, 0
	v_add3_u32 v235, s44, v233, v164
	s_nop 0
	ds_read_b128 v[64:67], v235
	ds_read_b128 v[240:243], v235 offset:32
	ds_read_b128 v[244:247], v235 offset:64
	ds_read_b128 v[248:251], v235 offset:96
	s_waitcnt lgkmcnt(3)
	v_mfma_f32_32x32x16_bf16 v[64:79], v[64:67], v[124:127], 0
	ds_read_b128 v[236:239], v235 offset:128
	s_waitcnt lgkmcnt(3)
	v_mfma_f32_32x32x16_bf16 v[64:79], v[240:243], v[120:123], v[64:79]
	ds_read_b128 v[240:243], v235 offset:160
	s_waitcnt lgkmcnt(3)
	v_mfma_f32_32x32x16_bf16 v[64:79], v[244:247], v[116:119], v[64:79]
	ds_read_b128 v[244:247], v235 offset:192
	s_waitcnt lgkmcnt(3)
	v_mfma_f32_32x32x16_bf16 v[64:79], v[248:251], v[112:115], v[64:79]
	ds_read_b128 v[248:251], v235 offset:224
	s_waitcnt lgkmcnt(3)
	v_mfma_f32_32x32x16_bf16 v[64:79], v[236:239], v[108:111], v[64:79]
	ds_read_b128 v[236:239], v235 offset:256
	s_waitcnt lgkmcnt(3)
	v_mfma_f32_32x32x16_bf16 v[64:79], v[240:243], v[104:107], v[64:79]
	ds_read_b128 v[240:243], v235 offset:288
	s_waitcnt lgkmcnt(3)
	v_mfma_f32_32x32x16_bf16 v[64:79], v[244:247], v[100:103], v[64:79]
	ds_read_b128 v[244:247], v235 offset:320
	s_waitcnt lgkmcnt(3)
	v_mfma_f32_32x32x16_bf16 v[64:79], v[248:251], v[96:99], v[64:79]
	ds_read_b128 v[248:251], v235 offset:352
	s_waitcnt lgkmcnt(3)
	v_mfma_f32_32x32x16_bf16 v[64:79], v[236:239], v[84:87], v[64:79]
	s_waitcnt lgkmcnt(2)
	v_mfma_f32_32x32x16_bf16 v[64:79], v[240:243], v[88:91], v[64:79]
	s_waitcnt lgkmcnt(1)
	v_mfma_f32_32x32x16_bf16 v[64:79], v[244:247], v[92:95], v[64:79]
	s_waitcnt lgkmcnt(0)
	v_mfma_f32_32x32x16_bf16 v[64:79], v[248:251], v[80:83], v[64:79]
	s_nop 0
	s_nop 10
	v_max_f32_e32 v235, v65, v65
	v_max_f32_e32 v236, v64, v64
	v_max_f32_e32 v235, v236, v235
	v_max3_f32 v235, v235, v66, v67
	v_max3_f32 v235, v235, v68, v69
	v_max3_f32 v235, v235, v70, v71
	v_max3_f32 v235, v235, v72, v73
	v_max3_f32 v235, v235, v74, v75
	v_max3_f32 v235, v235, v76, v77
	v_max3_f32 v235, v235, v78, v79
	ds_bpermute_b32 v236, v165, v235
	s_waitcnt lgkmcnt(0)
	v_max_f32_e32 v236, v236, v236
	v_max_f32_e32 v235, v235, v236
	v_add_f32_e32 v236, 0x41000000, v214
	v_cmp_gt_f32_e32 vcc, v235, v236
	s_cbranch_vccz .LBB0_593
; #define LAS __attribute__((address_space(3)))
; #define ATT_LOAD(t) do { _Pragma("unroll") for (int j = 0; j < 3; ++j) { const int id = tid + 512 * j; const int ch = id % 24; kreg[j] = *(const u32x4*)(ksrc[j] + (size_t)(t) * (ch < 16 ? kstep_n : kstep_p)); } \
;         _Pragma("unroll") for (int j = 0; j < 2; ++j) vreg[j] = *(const u32x4*)(vsrc[j] + (size_t)(t) * 8192); } while (0)
; #define ATT_STORE(buf) do { LAS unsigned char* kb_ = lds + (buf) * ATT_STAGE; LAS unsigned char* vb_ = kb_ + KBUF_B; \
;         _Pragma("unroll") for (int j = 0; j < 3; ++j) *(LAS u32x4*)(kb_ + kdst[j]) = kreg[j]; \
;         _Pragma("unroll") for (int j = 0; j < 2; ++j) *(LAS u32x4*)(vb_ + vdst[j]) = vreg[j]; } while (0)
; DI void attn_item(LAS unsigned char* lds, int bh, int qb, const bf16_t* QH, const bf16_t* KN, const bf16_t* KPE, const bf16_t* VT, const bf16_t* P, bf16_t* MIX) {
;     ...
;     for (int t = 0; t < ntile; ++t) {
;         __syncthreads();
;         if (t + 1 < ntile) { ATT_STORE((t + 1) & 1); if (t + 2 < ntile) ATT_LOAD(t + 2); }
;         LAS unsigned char* kb = lds + (t & 1) * ATT_STAGE; LAS unsigned char* vb = kb + KBUF_B;
;         f32x16 S;
; #pragma unroll
;         for (int i = 0; i < 16; ++i) S[i] = 0.f;
;         { const LAS unsigned char* kp = kb + (kh * 32 + r) * KROW + 16 * h2;
;           __builtin_amdgcn_s_setprio(1);
; #pragma unroll
;           for (int ks = 0; ks < 12; ++ks) { const bf16x8 a = *(const LAS bf16x8*)(kp + 32 * ks); S = __builtin_amdgcn_mfma_f32_32x32x16_bf16(a, Qf[ks], S, 0, 0, 0); }
;           __builtin_amdgcn_sched_group_barrier(0x100, 4, 0);
; #pragma unroll
;           for (int i = 0; i < 8; ++i) { __builtin_amdgcn_sched_group_barrier(0x008, 1, 0); __builtin_amdgcn_sched_group_barrier(0x100, 1, 0); }
;           __builtin_amdgcn_sched_group_barrier(0x008, 4, 0);
;           __builtin_amdgcn_s_setprio(0); }
;         const bool diag = (t >= 2 * qb);
;         if (diag) {
;             const int key0 = t * 64 + kh * 32 + 4 * h2;
; #pragma unroll
;             for (int i = 0; i < 16; ++i) { const int key = key0 + (i & 3) + 8 * (i >> 2); if (key > qpos) S[i] = NEG; }
	v_max_f32_e32 v235, v235, v235
	v_max_f32_e32 v236, v214, v214
	v_max_f32_e32 v235, v236, v235
	v_sub_f32_e32 v214, v214, v235
	v_exp_f32_e32 v214, v214
	s_nop 0
	v_pk_mul_f32 v[62:63], v[62:63], v[214:215] op_sel_hi:[1,0]
	v_pk_mul_f32 v[60:61], v[60:61], v[214:215] op_sel_hi:[1,0]
	v_pk_mul_f32 v[58:59], v[58:59], v[214:215] op_sel_hi:[1,0]
	v_pk_mul_f32 v[56:57], v[56:57], v[214:215] op_sel_hi:[1,0]
	v_pk_mul_f32 v[54:55], v[54:55], v[214:215] op_sel_hi:[1,0]
	v_pk_mul_f32 v[52:53], v[52:53], v[214:215] op_sel_hi:[1,0]
	v_pk_mul_f32 v[50:51], v[50:51], v[214:215] op_sel_hi:[1,0]
	v_pk_mul_f32 v[48:49], v[48:49], v[214:215] op_sel_hi:[1,0]
	v_pk_mul_f32 v[46:47], v[46:47], v[214:215] op_sel_hi:[1,0]
	v_pk_mul_f32 v[44:45], v[44:45], v[214:215] op_sel_hi:[1,0]
	v_pk_mul_f32 v[42:43], v[42:43], v[214:215] op_sel_hi:[1,0]
	v_pk_mul_f32 v[40:41], v[40:41], v[214:215] op_sel_hi:[1,0]
	v_pk_mul_f32 v[38:39], v[38:39], v[214:215] op_sel_hi:[1,0]
	v_pk_mul_f32 v[36:37], v[36:37], v[214:215] op_sel_hi:[1,0]
	v_pk_mul_f32 v[34:35], v[34:35], v[214:215] op_sel_hi:[1,0]
	v_pk_mul_f32 v[32:33], v[32:33], v[214:215] op_sel_hi:[1,0]
	v_pk_mul_f32 v[30:31], v[30:31], v[214:215] op_sel_hi:[1,0]
	v_pk_mul_f32 v[28:29], v[28:29], v[214:215] op_sel_hi:[1,0]
	v_pk_mul_f32 v[26:27], v[26:27], v[214:215] op_sel_hi:[1,0]
	v_pk_mul_f32 v[24:25], v[24:25], v[214:215] op_sel_hi:[1,0]
	v_pk_mul_f32 v[22:23], v[22:23], v[214:215] op_sel_hi:[1,0]
	v_pk_mul_f32 v[20:21], v[20:21], v[214:215] op_sel_hi:[1,0]
	v_pk_mul_f32 v[18:19], v[18:19], v[214:215] op_sel_hi:[1,0]
	v_pk_mul_f32 v[16:17], v[16:17], v[214:215] op_sel_hi:[1,0]
	v_pk_mul_f32 v[14:15], v[14:15], v[214:215] op_sel_hi:[1,0]
	v_pk_mul_f32 v[12:13], v[12:13], v[214:215] op_sel_hi:[1,0]
	v_pk_mul_f32 v[10:11], v[10:11], v[214:215] op_sel_hi:[1,0]
	v_pk_mul_f32 v[8:9], v[8:9], v[214:215] op_sel_hi:[1,0]
	v_pk_mul_f32 v[6:7], v[6:7], v[214:215] op_sel_hi:[1,0]
	v_pk_mul_f32 v[4:5], v[4:5], v[214:215] op_sel_hi:[1,0]
	v_pk_mul_f32 v[2:3], v[2:3], v[214:215] op_sel_hi:[1,0]
	v_pk_mul_f32 v[0:1], v[0:1], v[214:215] op_sel_hi:[1,0]
	v_mul_f32_e32 v234, v234, v214
	v_mov_b32_e32 v214, v235
	s_branch .LBB0_593
.LBB0_596:
	v_or_b32_e32 v216, s39, v232
	s_add_i32 s39, 0, 0xb400
	v_add_u32_e32 v64, s39, v171
	s_barrier
	s_waitcnt vmcnt(4)
	ds_write_b128 v64, v[128:131]
	v_add_u32_e32 v64, s39, v173
	s_waitcnt vmcnt(3)
	ds_write_b128 v64, v[132:135]
	v_add_u32_e32 v64, s39, v220
	s_waitcnt vmcnt(2)
	ds_write_b128 v64, v[144:147]
	v_add_u32_e32 v64, s39, v221
	s_add_i32 s43, s22, -2
	v_or_b32_e32 v217, s42, v223
	s_waitcnt vmcnt(1)
	ds_write_b128 v64, v[136:139] offset:25600
	v_add_u32_e32 v64, s39, v222
	s_waitcnt vmcnt(0)
	ds_write_b128 v64, v[140:143] offset:25600
	v_add3_u32 v144, s40, v233, v164
	s_nop 0
	ds_read_b128 v[64:67], v144
	ds_read_b128 v[128:131], v144 offset:32
	ds_read_b128 v[132:135], v144 offset:64
	ds_read_b128 v[136:139], v144 offset:96
	s_waitcnt lgkmcnt(3)
	v_mfma_f32_32x32x16_bf16 v[64:79], v[64:67], v[124:127], 0
	ds_read_b128 v[140:143], v144 offset:128
	s_waitcnt lgkmcnt(3)
	v_mfma_f32_32x32x16_bf16 v[64:79], v[128:131], v[120:123], v[64:79]
	ds_read_b128 v[128:131], v144 offset:160
	s_waitcnt lgkmcnt(3)
	v_mfma_f32_32x32x16_bf16 v[64:79], v[132:135], v[116:119], v[64:79]
	ds_read_b128 v[132:135], v144 offset:192
	s_waitcnt lgkmcnt(3)
	v_mfma_f32_32x32x16_bf16 v[64:79], v[136:139], v[112:115], v[64:79]
	ds_read_b128 v[136:139], v144 offset:224
	s_waitcnt lgkmcnt(3)
	v_mfma_f32_32x32x16_bf16 v[64:79], v[140:143], v[108:111], v[64:79]
	ds_read_b128 v[140:143], v144 offset:256
	s_waitcnt lgkmcnt(3)
	v_mfma_f32_32x32x16_bf16 v[64:79], v[128:131], v[104:107], v[64:79]
	ds_read_b128 v[128:131], v144 offset:288
	s_waitcnt lgkmcnt(3)
	v_mfma_f32_32x32x16_bf16 v[64:79], v[132:135], v[100:103], v[64:79]
	ds_read_b128 v[132:135], v144 offset:320
	s_waitcnt lgkmcnt(3)
	v_mfma_f32_32x32x16_bf16 v[64:79], v[136:139], v[96:99], v[64:79]
	ds_read_b128 v[136:139], v144 offset:352
	s_waitcnt lgkmcnt(3)
	v_mfma_f32_32x32x16_bf16 v[64:79], v[140:143], v[84:87], v[64:79]
	s_waitcnt lgkmcnt(2)
	v_mfma_f32_32x32x16_bf16 v[64:79], v[128:131], v[88:91], v[64:79]
	s_waitcnt lgkmcnt(1)
	v_mfma_f32_32x32x16_bf16 v[64:79], v[132:135], v[92:95], v[64:79]
	s_waitcnt lgkmcnt(0)
	v_mfma_f32_32x32x16_bf16 v[64:79], v[136:139], v[80:83], v[64:79]
	s_nop 0
	s_cmp_ge_u32 s43, s41
	s_cselect_b64 s[22:23], -1, 0
	s_cmp_lt_u32 s43, s41
	s_cbranch_scc1 .LBB0_598
	v_lshl_add_u32 v128, s43, 6, v217
	v_cmp_lt_u32_e32 vcc, v128, v216
	v_or_b32_e32 v129, 2, v128
	s_nop 3
	v_cndmask_b32_e32 v65, v230, v65, vcc
	v_cmp_le_u32_e32 vcc, v128, v216
	s_nop 1
	v_cndmask_b32_e32 v64, v230, v64, vcc
	v_cmp_le_u32_e32 vcc, v129, v216
	v_or_b32_e32 v129, 3, v128
	s_nop 0
	v_cndmask_b32_e32 v66, v230, v66, vcc
	v_cmp_le_u32_e32 vcc, v129, v216
	v_or_b32_e32 v129, 8, v128
	s_nop 0
	v_cndmask_b32_e32 v67, v230, v67, vcc
	v_cmp_le_u32_e32 vcc, v129, v216
	v_or_b32_e32 v129, 9, v128
	s_nop 0
	v_cndmask_b32_e32 v68, v230, v68, vcc
	v_cmp_le_u32_e32 vcc, v129, v216
	v_or_b32_e32 v129, 10, v128
	s_nop 0
	v_cndmask_b32_e32 v69, v230, v69, vcc
	v_cmp_le_u32_e32 vcc, v129, v216
	v_or_b32_e32 v129, 11, v128
	s_nop 0
	v_cndmask_b32_e32 v70, v230, v70, vcc
	v_cmp_le_u32_e32 vcc, v129, v216
	v_or_b32_e32 v129, 16, v128
	s_nop 0
	v_cndmask_b32_e32 v71, v230, v71, vcc
	v_cmp_le_u32_e32 vcc, v129, v216
	v_or_b32_e32 v129, 17, v128
	s_nop 0
	v_cndmask_b32_e32 v72, v230, v72, vcc
	v_cmp_le_u32_e32 vcc, v129, v216
	v_or_b32_e32 v129, 18, v128
	s_nop 0
	v_cndmask_b32_e32 v73, v230, v73, vcc
	v_cmp_le_u32_e32 vcc, v129, v216
	v_or_b32_e32 v129, 19, v128
	s_nop 0
	v_cndmask_b32_e32 v74, v230, v74, vcc
	v_cmp_le_u32_e32 vcc, v129, v216
	v_or_b32_e32 v129, 24, v128
	s_nop 0
	v_cndmask_b32_e32 v75, v230, v75, vcc
	v_cmp_le_u32_e32 vcc, v129, v216
	v_or_b32_e32 v129, 25, v128
	s_nop 0
	v_cndmask_b32_e32 v76, v230, v76, vcc
	v_cmp_le_u32_e32 vcc, v129, v216
	v_or_b32_e32 v129, 26, v128
	v_or_b32_e32 v128, 27, v128
	v_cndmask_b32_e32 v77, v230, v77, vcc
	v_cmp_le_u32_e32 vcc, v129, v216
	s_nop 1
	v_cndmask_b32_e32 v78, v230, v78, vcc
	v_cmp_le_u32_e32 vcc, v128, v216
	s_nop 1
	v_cndmask_b32_e32 v79, v230, v79, vcc

; #define LAS __attribute__((address_space(3)))
; DI unsigned pk2(float lo, float hi) { f32x2 v = {lo, hi}; bf2_t b = __builtin_convertvector(v, bf2_t); return __builtin_bit_cast(unsigned, b); }
; DI float fexp2(float x) { return __builtin_amdgcn_exp2f(x); }
; DI void attn_item(LAS unsigned char* lds, int bh, int qb, const bf16_t* QH, const bf16_t* KN, const bf16_t* KPE, const bf16_t* VT, const bf16_t* P, bf16_t* MIX) {
;     ...
;         float ps = 0.f;
; #pragma unroll
;         for (int i = 0; i < 16; ++i) { float p = fexp2(S[i] - mrow); if (diag && S[i] == NEG) p = 0.f; S[i] = p; ps += p; }
;         lrow += ps;
;         bf16x8 pb[2];
; #pragma unroll
;         for (int s2 = 0; s2 < 2; ++s2) { u32x4 w; w.x = pk2(S[8 * s2 + 0], S[8 * s2 + 1]); w.y = pk2(S[8 * s2 + 2], S[8 * s2 + 3]); w.z = pk2(S[8 * s2 + 4], S[8 * s2 + 5]); w.w = pk2(S[8 * s2 + 6], S[8 * s2 + 7]); pb[s2] = __builtin_bit_cast(bf16x8, w); }
;         __builtin_amdgcn_s_setprio(1);
;         {
;             const int li = lane & 15, gd = (lane >> 4) & 1;
;             const LAS unsigned char* vp = vb + (kh * 32 + 4 * h2 + (li >> 2)) * VROW + gd * 32 + (li & 3) * 8;
; #pragma unroll
;             for (int d = 0; d < 4; ++d)
; #pragma unroll
;                 for (int s2 = 0; s2 < 2; ++s2) {
;                     const s16x4 lo = __builtin_amdgcn_ds_read_tr16_b64_v4i16((LAS s16x4*)(vp + (16 * s2) * VROW + 64 * d));
;                     const s16x4 hi = __builtin_amdgcn_ds_read_tr16_b64_v4i16((LAS s16x4*)(vp + (16 * s2 + 8) * VROW + 64 * d));
;                     const bf16x8 av = __builtin_shufflevector(lo, hi, 0, 1, 2, 3, 4, 5, 6, 7);
;                     O[d] = __builtin_amdgcn_mfma_f32_32x32x16_bf16(av, pb[s2], O[d], 0, 0, 0);
;                 }
;         }
;         __builtin_amdgcn_s_setprio(0);
;     }
;     __syncthreads();
.LBB0_600:
	v_sub_f32_e32 v128, v64, v214
	v_exp_f32_e32 v128, v128
	v_cmp_eq_f32_e32 vcc, s30, v64
	s_and_b64 s[42:43], s[22:23], vcc
	v_cmp_eq_f32_e32 vcc, s30, v65
	v_cndmask_b32_e64 v64, v128, 0, s[42:43]
	v_sub_f32_e32 v128, v65, v214
	v_exp_f32_e32 v128, v128
	s_and_b64 s[42:43], s[22:23], vcc
	v_cmp_eq_f32_e32 vcc, s30, v66
	v_add_f32_e32 v130, 0, v64
	v_cndmask_b32_e64 v65, v128, 0, s[42:43]
	v_sub_f32_e32 v128, v66, v214
	v_exp_f32_e32 v128, v128
	s_and_b64 s[42:43], s[22:23], vcc
	v_cmp_eq_f32_e32 vcc, s30, v67
	v_add_f32_e32 v130, v65, v130
	v_cndmask_b32_e64 v66, v128, 0, s[42:43]
	v_sub_f32_e32 v128, v67, v214
	v_exp_f32_e32 v128, v128
	s_and_b64 s[42:43], s[22:23], vcc
	v_cmp_eq_f32_e32 vcc, s30, v68
	v_add_f32_e32 v130, v66, v130
	v_cndmask_b32_e64 v67, v128, 0, s[42:43]
	v_sub_f32_e32 v128, v68, v214
	v_exp_f32_e32 v128, v128
	s_and_b64 s[42:43], s[22:23], vcc
	v_cmp_eq_f32_e32 vcc, s30, v69
	v_add_f32_e32 v130, v67, v130
	v_cndmask_b32_e64 v68, v128, 0, s[42:43]
	v_sub_f32_e32 v128, v69, v214
	v_exp_f32_e32 v128, v128
	s_and_b64 s[42:43], s[22:23], vcc
	v_cmp_eq_f32_e32 vcc, s30, v70
	v_add_f32_e32 v130, v68, v130
	v_cndmask_b32_e64 v69, v128, 0, s[42:43]
	v_sub_f32_e32 v128, v70, v214
	v_exp_f32_e32 v128, v128
	s_and_b64 s[42:43], s[22:23], vcc
	v_cmp_eq_f32_e32 vcc, s30, v71
	v_add_f32_e32 v130, v69, v130
	v_cndmask_b32_e64 v70, v128, 0, s[42:43]
	v_sub_f32_e32 v128, v71, v214
	v_exp_f32_e32 v128, v128
	s_and_b64 s[42:43], s[22:23], vcc
	v_cmp_eq_f32_e32 vcc, s30, v72
	v_add_f32_e32 v130, v70, v130
	v_cndmask_b32_e64 v71, v128, 0, s[42:43]
	v_sub_f32_e32 v128, v72, v214
	v_exp_f32_e32 v128, v128
	s_and_b64 s[42:43], s[22:23], vcc
	v_cmp_eq_f32_e32 vcc, s30, v73
	v_add_f32_e32 v130, v71, v130
	v_cndmask_b32_e64 v72, v128, 0, s[42:43]
	v_sub_f32_e32 v128, v73, v214
	v_exp_f32_e32 v128, v128
	s_and_b64 s[42:43], s[22:23], vcc
	v_cmp_eq_f32_e32 vcc, s30, v74
	v_add_f32_e32 v130, v72, v130
	v_cndmask_b32_e64 v73, v128, 0, s[42:43]
	v_sub_f32_e32 v128, v74, v214
	v_exp_f32_e32 v128, v128
	s_and_b64 s[42:43], s[22:23], vcc
	v_cmp_eq_f32_e32 vcc, s30, v75
	v_add_f32_e32 v130, v73, v130
	v_cndmask_b32_e64 v74, v128, 0, s[42:43]
	v_sub_f32_e32 v128, v75, v214
	v_exp_f32_e32 v128, v128
	s_and_b64 s[42:43], s[22:23], vcc
	v_cmp_eq_f32_e32 vcc, s30, v76
	v_add_f32_e32 v130, v74, v130
	v_cndmask_b32_e64 v75, v128, 0, s[42:43]
	v_sub_f32_e32 v128, v76, v214
	v_exp_f32_e32 v128, v128
	s_and_b64 s[42:43], s[22:23], vcc
	v_cmp_eq_f32_e32 vcc, s30, v77
	v_add_f32_e32 v130, v75, v130
	v_cndmask_b32_e64 v76, v128, 0, s[42:43]
	v_sub_f32_e32 v128, v77, v214
	v_exp_f32_e32 v128, v128
	s_and_b64 s[42:43], s[22:23], vcc
	v_cmp_eq_f32_e32 vcc, s30, v78
	v_add_f32_e32 v130, v76, v130
	v_cndmask_b32_e64 v77, v128, 0, s[42:43]
	v_sub_f32_e32 v128, v78, v214
	v_exp_f32_e32 v128, v128
	s_and_b64 s[42:43], s[22:23], vcc
	v_cmp_eq_f32_e32 vcc, s30, v79
	v_add_f32_e32 v130, v77, v130
	v_cndmask_b32_e64 v78, v128, 0, s[42:43]
	v_sub_f32_e32 v128, v79, v214
	v_exp_f32_e32 v128, v128
	s_and_b64 s[22:23], s[22:23], vcc
	v_add_f32_e32 v130, v78, v130
	v_cvt_pk_bf16_f32 v64, v64, v65
	v_cndmask_b32_e64 v79, v128, 0, s[22:23]
	v_add_f32_e32 v128, v79, v130
	v_cvt_pk_bf16_f32 v65, v66, v67
	v_cvt_pk_bf16_f32 v66, v68, v69
	v_cvt_pk_bf16_f32 v67, v70, v71
	v_cvt_pk_bf16_f32 v68, v72, v73
	v_cvt_pk_bf16_f32 v69, v74, v75
	v_cvt_pk_bf16_f32 v70, v76, v77
	v_cvt_pk_bf16_f32 v71, v78, v79
	s_add_i32 s41, s41, -1
	s_nop 0
	v_add_u32_e32 v72, s40, v215
	v_add3_u32 v78, v72, v225, v226
	ds_read_b64_tr_b16 v[72:73], v78 offset:25600
	ds_read_b64_tr_b16 v[74:75], v78 offset:28160
	ds_read_b64_tr_b16 v[130:131], v78 offset:25664
	ds_read_b64_tr_b16 v[134:135], v78 offset:25728
	ds_read_b64_tr_b16 v[138:139], v78 offset:25792
	ds_read_b64_tr_b16 v[132:133], v78 offset:28224
	ds_read_b64_tr_b16 v[136:137], v78 offset:28288
	ds_read_b64_tr_b16 v[140:141], v78 offset:28352
	ds_read_b64_tr_b16 v[76:77], v78 offset:33280
	s_waitcnt lgkmcnt(7)
	v_mfma_f32_32x32x16_bf16 v[48:63], v[72:75], v[64:67], v[48:63]
	ds_read_b64_tr_b16 v[74:75], v78 offset:30720
	ds_read_b64_tr_b16 v[142:143], v78 offset:30784
	ds_read_b64_tr_b16 v[240:241], v78 offset:30848
	ds_read_b64_tr_b16 v[244:245], v78 offset:30912
	ds_read_b64_tr_b16 v[144:145], v78 offset:33344
	ds_read_b64_tr_b16 v[242:243], v78 offset:33408
	ds_read_b64_tr_b16 v[246:247], v78 offset:33472
	s_waitcnt lgkmcnt(10)
	v_mfma_f32_32x32x16_bf16 v[32:47], v[130:133], v[64:67], v[32:47]
	v_add_f32_e32 v128, v234, v128
	s_waitcnt lgkmcnt(9)
	v_mfma_f32_32x32x16_bf16 v[16:31], v[134:137], v[64:67], v[16:31]
	s_waitcnt lgkmcnt(8)
	v_mfma_f32_32x32x16_bf16 v[0:15], v[138:141], v[64:67], v[0:15]
	s_waitcnt lgkmcnt(6)
	v_mfma_f32_32x32x16_bf16 v[48:63], v[74:77], v[68:71], v[48:63]
	s_waitcnt lgkmcnt(2)
	v_mfma_f32_32x32x16_bf16 v[32:47], v[142:145], v[68:71], v[32:47]
	s_waitcnt lgkmcnt(1)
	v_mfma_f32_32x32x16_bf16 v[16:31], v[240:243], v[68:71], v[16:31]
	s_waitcnt lgkmcnt(0)
	v_mfma_f32_32x32x16_bf16 v[0:15], v[244:247], v[68:71], v[0:15]
	s_nop 0
	s_barrier
; #define LAS __attribute__((address_space(3)))
; DI float fexp2(float x) { return __builtin_amdgcn_exp2f(x); }
; DI void attn_item(LAS unsigned char* lds, int bh, int qb, const bf16_t* QH, const bf16_t* KN, const bf16_t* KPE, const bf16_t* VT, const bf16_t* P, bf16_t* MIX) {
;     ...
;         { const LAS unsigned char* kp = kb + (kh * 32 + r) * KROW + 16 * h2;
;           __builtin_amdgcn_s_setprio(1);
; #pragma unroll
;           for (int ks = 0; ks < 12; ++ks) { const bf16x8 a = *(const LAS bf16x8*)(kp + 32 * ks); S = __builtin_amdgcn_mfma_f32_32x32x16_bf16(a, Qf[ks], S, 0, 0, 0); }
;           __builtin_amdgcn_sched_group_barrier(0x100, 4, 0);
; #pragma unroll
;           for (int i = 0; i < 8; ++i) { __builtin_amdgcn_sched_group_barrier(0x008, 1, 0); __builtin_amdgcn_sched_group_barrier(0x100, 1, 0); }
;           __builtin_amdgcn_sched_group_barrier(0x008, 4, 0);
;           __builtin_amdgcn_s_setprio(0); }
;         const bool diag = (t >= 2 * qb);
;         if (diag) {
;             const int key0 = t * 64 + kh * 32 + 4 * h2;
; #pragma unroll
;             for (int i = 0; i < 16; ++i) { const int key = key0 + (i & 3) + 8 * (i >> 2); if (key > qpos) S[i] = NEG; }
;         }
;         float mx = S[0];
; #pragma unroll
;         for (int i = 1; i < 16; ++i) mx = fmaxf(mx, S[i]);
;         mx = fmaxf(mx, __shfl_xor(mx, 32));
;         if (__any(mx > mrow + 8.f)) {
;             const float mnew = fmaxf(mrow, mx);
;             const float alpha = fexp2(mrow - mnew);
;             mrow = mnew; lrow *= alpha;
; #pragma unroll
;             for (int d = 0; d < 4; ++d)
; #pragma unroll
;                 for (int i = 0; i < 16; ++i) O[d][i] *= alpha;
;         }
	v_add3_u32 v142, s39, v233, v164
	s_nop 0
	ds_read_b128 v[64:67], v142
	ds_read_b128 v[130:133], v142 offset:32
	ds_read_b128 v[134:137], v142 offset:64
	ds_read_b128 v[138:141], v142 offset:96
	s_waitcnt lgkmcnt(3)
	v_mfma_f32_32x32x16_bf16 v[64:79], v[64:67], v[124:127], 0
	ds_read_b128 v[124:127], v142 offset:128
	s_waitcnt lgkmcnt(3)
	v_mfma_f32_32x32x16_bf16 v[64:79], v[130:133], v[120:123], v[64:79]
	ds_read_b128 v[120:123], v142 offset:160
	s_waitcnt lgkmcnt(3)
	v_mfma_f32_32x32x16_bf16 v[64:79], v[134:137], v[116:119], v[64:79]
	ds_read_b128 v[116:119], v142 offset:192
	s_waitcnt lgkmcnt(3)
	v_mfma_f32_32x32x16_bf16 v[64:79], v[138:141], v[112:115], v[64:79]
	ds_read_b128 v[112:115], v142 offset:224
	s_waitcnt lgkmcnt(3)
	v_mfma_f32_32x32x16_bf16 v[64:79], v[124:127], v[108:111], v[64:79]
	ds_read_b128 v[108:111], v142 offset:256
	s_waitcnt lgkmcnt(3)
	v_mfma_f32_32x32x16_bf16 v[64:79], v[120:123], v[104:107], v[64:79]
	ds_read_b128 v[104:107], v142 offset:288
	s_waitcnt lgkmcnt(3)
	v_mfma_f32_32x32x16_bf16 v[64:79], v[116:119], v[100:103], v[64:79]
	ds_read_b128 v[100:103], v142 offset:320
	s_waitcnt lgkmcnt(3)
	v_mfma_f32_32x32x16_bf16 v[64:79], v[112:115], v[96:99], v[64:79]
	ds_read_b128 v[96:99], v142 offset:352
	s_waitcnt lgkmcnt(3)
	v_mfma_f32_32x32x16_bf16 v[64:79], v[108:111], v[84:87], v[64:79]
	s_waitcnt lgkmcnt(2)
	v_mfma_f32_32x32x16_bf16 v[64:79], v[104:107], v[88:91], v[64:79]
	s_waitcnt lgkmcnt(1)
	v_mfma_f32_32x32x16_bf16 v[64:79], v[100:103], v[92:95], v[64:79]
	s_waitcnt lgkmcnt(0)
	v_mfma_f32_32x32x16_bf16 v[64:79], v[96:99], v[80:83], v[64:79]
	s_nop 0
	s_lshl_b32 s22, s41, 6
	s_addk_i32 s22, 0x80
	v_add_u32_e32 v88, s22, v217
	v_cmp_le_u32_e32 vcc, v88, v216
	s_nop 6
	v_cndmask_b32_e32 v87, v230, v64, vcc
	v_cmp_lt_u32_e32 vcc, v88, v216
	v_or_b32_e32 v64, 2, v88
	s_nop 0
	v_cndmask_b32_e32 v86, v230, v65, vcc
	v_cmp_le_u32_e32 vcc, v64, v216
	v_or_b32_e32 v64, 3, v88
	v_or_b32_e32 v65, 27, v88
	v_cndmask_b32_e32 v84, v230, v66, vcc
	v_cmp_le_u32_e32 vcc, v64, v216
	v_or_b32_e32 v64, 8, v88
	s_nop 0
	v_cndmask_b32_e32 v85, v230, v67, vcc
	v_cmp_le_u32_e32 vcc, v64, v216
	v_or_b32_e32 v64, 9, v88
	s_nop 0
	v_cndmask_b32_e32 v82, v230, v68, vcc
	v_cmp_le_u32_e32 vcc, v64, v216
	v_or_b32_e32 v64, 10, v88
	s_nop 0
	v_cndmask_b32_e32 v83, v230, v69, vcc
	v_cmp_le_u32_e32 vcc, v64, v216
	v_or_b32_e32 v64, 11, v88
	s_nop 0
	v_cndmask_b32_e32 v80, v230, v70, vcc
	v_cmp_le_u32_e32 vcc, v64, v216
	v_or_b32_e32 v64, 16, v88
	s_nop 0
	v_cndmask_b32_e32 v81, v230, v71, vcc
	v_cmp_le_u32_e32 vcc, v64, v216
	v_or_b32_e32 v64, 17, v88
	s_nop 0
	v_cndmask_b32_e32 v70, v230, v72, vcc
	v_cmp_le_u32_e32 vcc, v64, v216
	v_or_b32_e32 v64, 18, v88
	v_max_f32_e32 v72, v86, v86
	v_cndmask_b32_e32 v71, v230, v73, vcc
	v_max_f32_e32 v73, v87, v87
	v_cmp_le_u32_e32 vcc, v64, v216
	v_or_b32_e32 v64, 19, v88
	v_max_f32_e32 v72, v73, v72
	v_cndmask_b32_e32 v68, v230, v74, vcc
	v_cmp_le_u32_e32 vcc, v64, v216
	v_or_b32_e32 v64, 24, v88
	v_max3_f32 v72, v72, v84, v85
	v_cndmask_b32_e32 v69, v230, v75, vcc
	v_cmp_le_u32_e32 vcc, v64, v216
	v_or_b32_e32 v64, 25, v88
	v_max3_f32 v72, v72, v82, v83
	v_cndmask_b32_e32 v66, v230, v76, vcc
	v_cmp_le_u32_e32 vcc, v64, v216
	v_or_b32_e32 v64, 26, v88
	v_max3_f32 v72, v72, v80, v81
	v_cndmask_b32_e32 v67, v230, v77, vcc
	v_cmp_le_u32_e32 vcc, v64, v216
	v_max3_f32 v72, v72, v70, v71
	v_max3_f32 v72, v72, v68, v69
	v_cndmask_b32_e32 v64, v230, v78, vcc
	v_cmp_le_u32_e32 vcc, v65, v216
	v_max3_f32 v72, v72, v66, v67
	s_nop 0
	v_cndmask_b32_e32 v65, v230, v79, vcc
	v_max3_f32 v72, v72, v64, v65
	ds_bpermute_b32 v73, v165, v72
	s_waitcnt lgkmcnt(0)
	v_max_f32_e32 v73, v73, v73
	v_max_f32_e32 v72, v72, v73
	v_cmp_gt_f32_e32 vcc, v72, v129
	s_cbranch_vccz .LBB0_602
	v_max_f32_e32 v72, v72, v72
	v_max_f32_e32 v73, v214, v214
	v_max_f32_e32 v73, v73, v72
	v_sub_f32_e32 v72, v214, v73
	v_exp_f32_e32 v72, v72
	v_mov_b32_e32 v214, v73
	v_pk_mul_f32 v[62:63], v[62:63], v[72:73] op_sel_hi:[1,0]
	v_pk_mul_f32 v[60:61], v[60:61], v[72:73] op_sel_hi:[1,0]
	v_pk_mul_f32 v[58:59], v[58:59], v[72:73] op_sel_hi:[1,0]
	v_pk_mul_f32 v[56:57], v[56:57], v[72:73] op_sel_hi:[1,0]
	v_pk_mul_f32 v[54:55], v[54:55], v[72:73] op_sel_hi:[1,0]
	v_pk_mul_f32 v[52:53], v[52:53], v[72:73] op_sel_hi:[1,0]
	v_pk_mul_f32 v[50:51], v[50:51], v[72:73] op_sel_hi:[1,0]
	v_pk_mul_f32 v[48:49], v[48:49], v[72:73] op_sel_hi:[1,0]
	v_pk_mul_f32 v[46:47], v[46:47], v[72:73] op_sel_hi:[1,0]
	v_pk_mul_f32 v[44:45], v[44:45], v[72:73] op_sel_hi:[1,0]
	v_pk_mul_f32 v[42:43], v[42:43], v[72:73] op_sel_hi:[1,0]
	v_pk_mul_f32 v[40:41], v[40:41], v[72:73] op_sel_hi:[1,0]
	v_pk_mul_f32 v[38:39], v[38:39], v[72:73] op_sel_hi:[1,0]
	v_pk_mul_f32 v[36:37], v[36:37], v[72:73] op_sel_hi:[1,0]
	v_pk_mul_f32 v[34:35], v[34:35], v[72:73] op_sel_hi:[1,0]
	v_pk_mul_f32 v[32:33], v[32:33], v[72:73] op_sel_hi:[1,0]
	v_pk_mul_f32 v[30:31], v[30:31], v[72:73] op_sel_hi:[1,0]
	v_pk_mul_f32 v[28:29], v[28:29], v[72:73] op_sel_hi:[1,0]
	v_pk_mul_f32 v[26:27], v[26:27], v[72:73] op_sel_hi:[1,0]
	v_pk_mul_f32 v[24:25], v[24:25], v[72:73] op_sel_hi:[1,0]
	v_pk_mul_f32 v[22:23], v[22:23], v[72:73] op_sel_hi:[1,0]
	v_pk_mul_f32 v[20:21], v[20:21], v[72:73] op_sel_hi:[1,0]
	v_pk_mul_f32 v[18:19], v[18:19], v[72:73] op_sel_hi:[1,0]
	v_pk_mul_f32 v[16:17], v[16:17], v[72:73] op_sel_hi:[1,0]
	v_pk_mul_f32 v[14:15], v[14:15], v[72:73] op_sel_hi:[1,0]
	v_pk_mul_f32 v[12:13], v[12:13], v[72:73] op_sel_hi:[1,0]
	v_pk_mul_f32 v[10:11], v[10:11], v[72:73] op_sel_hi:[1,0]
	v_pk_mul_f32 v[8:9], v[8:9], v[72:73] op_sel_hi:[1,0]
	v_pk_mul_f32 v[6:7], v[6:7], v[72:73] op_sel_hi:[1,0]
	v_pk_mul_f32 v[4:5], v[4:5], v[72:73] op_sel_hi:[1,0]
	v_pk_mul_f32 v[2:3], v[2:3], v[72:73] op_sel_hi:[1,0]
	v_pk_mul_f32 v[0:1], v[0:1], v[72:73] op_sel_hi:[1,0]
	v_mul_f32_e32 v128, v128, v72
; #define LAS __attribute__((address_space(3)))
; DI unsigned pk2(float lo, float hi) { f32x2 v = {lo, hi}; bf2_t b = __builtin_convertvector(v, bf2_t); return __builtin_bit_cast(unsigned, b); }
; DI float fexp2(float x) { return __builtin_amdgcn_exp2f(x); }
; DI void attn_item(LAS unsigned char* lds, int bh, int qb, const bf16_t* QH, const bf16_t* KN, const bf16_t* KPE, const bf16_t* VT, const bf16_t* P, bf16_t* MIX) {
;     ...
;         float ps = 0.f;
; #pragma unroll
;         for (int i = 0; i < 16; ++i) { float p = fexp2(S[i] - mrow); if (diag && S[i] == NEG) p = 0.f; S[i] = p; ps += p; }
;         lrow += ps;
;         bf16x8 pb[2];
; #pragma unroll
;         for (int s2 = 0; s2 < 2; ++s2) { u32x4 w; w.x = pk2(S[8 * s2 + 0], S[8 * s2 + 1]); w.y = pk2(S[8 * s2 + 2], S[8 * s2 + 3]); w.z = pk2(S[8 * s2 + 4], S[8 * s2 + 5]); w.w = pk2(S[8 * s2 + 6], S[8 * s2 + 7]); pb[s2] = __builtin_bit_cast(bf16x8, w); }
;         __builtin_amdgcn_s_setprio(1);
;         {
;             const int li = lane & 15, gd = (lane >> 4) & 1;
;             const LAS unsigned char* vp = vb + (kh * 32 + 4 * h2 + (li >> 2)) * VROW + gd * 32 + (li & 3) * 8;
; #pragma unroll
;             for (int d = 0; d < 4; ++d)
; #pragma unroll
;                 for (int s2 = 0; s2 < 2; ++s2) {
;                     const s16x4 lo = __builtin_amdgcn_ds_read_tr16_b64_v4i16((LAS s16x4*)(vp + (16 * s2) * VROW + 64 * d));
;                     const s16x4 hi = __builtin_amdgcn_ds_read_tr16_b64_v4i16((LAS s16x4*)(vp + (16 * s2 + 8) * VROW + 64 * d));
;                     const bf16x8 av = __builtin_shufflevector(lo, hi, 0, 1, 2, 3, 4, 5, 6, 7);
;                     O[d] = __builtin_amdgcn_mfma_f32_32x32x16_bf16(av, pb[s2], O[d], 0, 0, 0);
;                 }
;         }
;         __builtin_amdgcn_s_setprio(0);
;     }
;     __syncthreads();
;     ...
;     lrow += __shfl_xor(lrow, 32);
;     LAS float* mb = (LAS float*)lds + (rg * 64 + lane) * 66;
;     if (kh == 1) {
; #pragma unroll
;         for (int d = 0; d < 4; ++d)
; #pragma unroll
;             for (int i = 0; i < 16; ++i) mb[d * 16 + i] = O[d][i];
;         mb[64] = mrow; mb[65] = lrow;
.LBB0_602:
	v_sub_f32_e32 v72, v87, v214
	v_exp_f32_e32 v72, v72
	v_sub_f32_e32 v73, v86, v214
	v_exp_f32_e32 v73, v73
	v_sub_f32_e32 v75, v84, v214
	v_exp_f32_e32 v75, v75
	v_sub_f32_e32 v76, v85, v214
	v_cmp_neq_f32_e32 vcc, s30, v87
	v_exp_f32_e32 v76, v76
	v_sub_f32_e32 v77, v82, v214
	v_cndmask_b32_e32 v72, 0, v72, vcc
	v_cmp_neq_f32_e32 vcc, s30, v86
	v_exp_f32_e32 v77, v77
	v_sub_f32_e32 v78, v83, v214
	v_cndmask_b32_e32 v73, 0, v73, vcc
	v_cmp_neq_f32_e32 vcc, s30, v84
	v_exp_f32_e32 v78, v78
	v_sub_f32_e32 v79, v80, v214
	v_cndmask_b32_e32 v75, 0, v75, vcc
	v_cmp_neq_f32_e32 vcc, s30, v85
	v_exp_f32_e32 v79, v79
	v_add_f32_e32 v74, 0, v72
	v_cndmask_b32_e32 v76, 0, v76, vcc
	v_cmp_neq_f32_e32 vcc, s30, v82
	v_sub_f32_e32 v82, v81, v214
	v_exp_f32_e32 v82, v82
	v_cndmask_b32_e32 v77, 0, v77, vcc
	v_cmp_neq_f32_e32 vcc, s30, v83
	v_add_f32_e32 v74, v73, v74
	v_add_f32_e32 v74, v75, v74
	v_cndmask_b32_e32 v78, 0, v78, vcc
	v_cmp_neq_f32_e32 vcc, s30, v80
	v_add_f32_e32 v74, v76, v74
	v_add_f32_e32 v74, v77, v74
	v_cndmask_b32_e32 v79, 0, v79, vcc
	v_cmp_neq_f32_e32 vcc, s30, v81
	v_sub_f32_e32 v81, v70, v214
	v_exp_f32_e32 v81, v81
	v_cndmask_b32_e32 v80, 0, v82, vcc
	v_sub_f32_e32 v82, v71, v214
	v_cmp_neq_f32_e32 vcc, s30, v70
	v_exp_f32_e32 v82, v82
	v_add_f32_e32 v74, v78, v74
	v_cndmask_b32_e32 v70, 0, v81, vcc
	v_sub_f32_e32 v81, v68, v214
	v_exp_f32_e32 v81, v81
	v_add_f32_e32 v74, v79, v74
	v_add_f32_e32 v74, v80, v74
	v_cmp_neq_f32_e32 vcc, s30, v71
	v_add_f32_e32 v74, v70, v74
	s_nop 0
	v_cndmask_b32_e32 v71, 0, v82, vcc
	v_cmp_neq_f32_e32 vcc, s30, v68
	v_add_f32_e32 v74, v71, v74
	v_sub_f32_e32 v82, v69, v214
	v_cndmask_b32_e32 v81, 0, v81, vcc
	v_exp_f32_e32 v82, v82
	v_add_f32_e32 v68, v81, v74
	v_sub_f32_e32 v74, v66, v214
	v_exp_f32_e32 v74, v74
	v_cmp_neq_f32_e32 vcc, s30, v69
	s_nop 1
	v_cndmask_b32_e32 v69, 0, v82, vcc
	v_sub_f32_e32 v82, v67, v214
	v_cmp_neq_f32_e32 vcc, s30, v66
	v_add_f32_e32 v68, v69, v68
	v_exp_f32_e32 v82, v82
	v_cndmask_b32_e32 v74, 0, v74, vcc
	v_cmp_neq_f32_e32 vcc, s30, v67
	v_sub_f32_e32 v67, v64, v214
	v_add_f32_e32 v66, v74, v68
	v_exp_f32_e32 v67, v67
	v_sub_f32_e32 v68, v65, v214
	v_exp_f32_e32 v68, v68
	v_cndmask_b32_e32 v82, 0, v82, vcc
	v_cmp_neq_f32_e32 vcc, s30, v64
	v_add_f32_e32 v66, v82, v66
	v_cvt_pk_bf16_f32 v69, v81, v69
	v_cndmask_b32_e32 v83, 0, v67, vcc
	v_cmp_neq_f32_e32 vcc, s30, v65
	v_add_f32_e32 v64, v83, v66
	v_cvt_pk_bf16_f32 v67, v79, v80
	v_cndmask_b32_e32 v84, 0, v68, vcc
	v_add_f32_e32 v102, v84, v64
	v_cvt_pk_bf16_f32 v64, v72, v73
	v_cvt_pk_bf16_f32 v65, v75, v76
	v_cvt_pk_bf16_f32 v66, v77, v78
	v_cvt_pk_bf16_f32 v68, v70, v71
	v_cvt_pk_bf16_f32 v70, v74, v82
	v_cvt_pk_bf16_f32 v71, v83, v84
	s_nop 0
	v_add_u32_e32 v72, s39, v215
	v_add3_u32 v100, v72, v225, v226
	ds_read_b64_tr_b16 v[72:73], v100 offset:25600
	ds_read_b64_tr_b16 v[74:75], v100 offset:28160
	ds_read_b64_tr_b16 v[76:77], v100 offset:33280
	ds_read_b64_tr_b16 v[78:79], v100 offset:25664
	ds_read_b64_tr_b16 v[82:83], v100 offset:25728
	ds_read_b64_tr_b16 v[86:87], v100 offset:25792
	ds_read_b64_tr_b16 v[80:81], v100 offset:28224
	ds_read_b64_tr_b16 v[84:85], v100 offset:28288
	ds_read_b64_tr_b16 v[88:89], v100 offset:28352
	s_waitcnt lgkmcnt(7)
	v_mfma_f32_32x32x16_bf16 v[48:63], v[72:75], v[64:67], v[48:63]
	ds_read_b64_tr_b16 v[74:75], v100 offset:30720
	ds_read_b64_tr_b16 v[90:91], v100 offset:30784
	ds_read_b64_tr_b16 v[94:95], v100 offset:30848
	ds_read_b64_tr_b16 v[98:99], v100 offset:30912
	ds_read_b64_tr_b16 v[92:93], v100 offset:33344
	ds_read_b64_tr_b16 v[96:97], v100 offset:33408
	ds_read_b64_tr_b16 v[100:101], v100 offset:33472
	s_waitcnt lgkmcnt(9)
	v_mfma_f32_32x32x16_bf16 v[32:47], v[78:81], v[64:67], v[32:47]
	s_waitcnt lgkmcnt(8)
	v_mfma_f32_32x32x16_bf16 v[16:31], v[82:85], v[64:67], v[16:31]
	s_waitcnt lgkmcnt(7)
	v_mfma_f32_32x32x16_bf16 v[0:15], v[86:89], v[64:67], v[0:15]
	v_add_f32_e32 v64, v128, v102
	s_waitcnt lgkmcnt(6)
	v_mfma_f32_32x32x16_bf16 v[48:63], v[74:77], v[68:71], v[48:63]
	s_waitcnt lgkmcnt(2)
	v_mfma_f32_32x32x16_bf16 v[32:47], v[90:93], v[68:71], v[32:47]
	s_waitcnt lgkmcnt(1)
	v_mfma_f32_32x32x16_bf16 v[16:31], v[94:97], v[68:71], v[16:31]
	s_waitcnt lgkmcnt(0)
	v_mfma_f32_32x32x16_bf16 v[0:15], v[98:101], v[68:71], v[0:15]
	s_nop 0
	ds_bpermute_b32 v65, v165, v64
	v_lshl_or_b32 v66, s37, 6, v252
	s_cmp_lg_u32 s38, 1
	v_mad_u32_u24 v67, v66, s31, 0
	s_waitcnt lgkmcnt(0)
	v_add_f32_e32 v215, v64, v65
	s_barrier
	s_cbranch_scc1 .LBB0_604
	ds_write2_b64 v67, v[48:49], v[50:51] offset1:1
	ds_write2_b64 v67, v[52:53], v[54:55] offset0:2 offset1:3
	ds_write2_b64 v67, v[56:57], v[58:59] offset0:4 offset1:5
	ds_write2_b64 v67, v[60:61], v[62:63] offset0:6 offset1:7
	ds_write2_b64 v67, v[32:33], v[34:35] offset0:8 offset1:9
	ds_write2_b64 v67, v[36:37], v[38:39] offset0:10 offset1:11
	ds_write2_b64 v67, v[40:41], v[42:43] offset0:12 offset1:13
	ds_write2_b64 v67, v[44:45], v[46:47] offset0:14 offset1:15
	ds_write2_b64 v67, v[16:17], v[18:19] offset0:16 offset1:17
	ds_write2_b64 v67, v[20:21], v[22:23] offset0:18 offset1:19
	ds_write2_b64 v67, v[24:25], v[26:27] offset0:20 offset1:21
	ds_write2_b64 v67, v[28:29], v[30:31] offset0:22 offset1:23
	ds_write2_b64 v67, v[0:1], v[2:3] offset0:24 offset1:25
	ds_write2_b64 v67, v[4:5], v[6:7] offset0:26 offset1:27
	ds_write2_b64 v67, v[8:9], v[10:11] offset0:28 offset1:29
	ds_write2_b64 v67, v[12:13], v[14:15] offset0:30 offset1:31
	ds_write_b64 v67, v[214:215] offset:256

; #define LAS __attribute__((address_space(3)))
; DI unsigned pk2(float lo, float hi) { f32x2 v = {lo, hi}; bf2_t b = __builtin_convertvector(v, bf2_t); return __builtin_bit_cast(unsigned, b); }
; DI float fexp2(float x) { return __builtin_amdgcn_exp2f(x); }
; DI void attn_item(LAS unsigned char* lds, int bh, int qb, const bf16_t* QH, const bf16_t* KN, const bf16_t* KPE, const bf16_t* VT, const bf16_t* P, bf16_t* MIX) {
;     ...
;         float ps = 0.f;
; #pragma unroll
;         for (int i = 0; i < 16; ++i) { float p = fexp2(S[i] - mrow); if (diag && S[i] == NEG) p = 0.f; S[i] = p; ps += p; }
;         lrow += ps;
;         bf16x8 pb[2];
; #pragma unroll
;         for (int s2 = 0; s2 < 2; ++s2) { u32x4 w; w.x = pk2(S[8 * s2 + 0], S[8 * s2 + 1]); w.y = pk2(S[8 * s2 + 2], S[8 * s2 + 3]); w.z = pk2(S[8 * s2 + 4], S[8 * s2 + 5]); w.w = pk2(S[8 * s2 + 6], S[8 * s2 + 7]); pb[s2] = __builtin_bit_cast(bf16x8, w); }
;         __builtin_amdgcn_s_setprio(1);
;         {
;             const int li = lane & 15, gd = (lane >> 4) & 1;
;             const LAS unsigned char* vp = vb + (kh * 32 + 4 * h2 + (li >> 2)) * VROW + gd * 32 + (li & 3) * 8;
; #pragma unroll
;             for (int d = 0; d < 4; ++d)
; #pragma unroll
;                 for (int s2 = 0; s2 < 2; ++s2) {
;                     const s16x4 lo = __builtin_amdgcn_ds_read_tr16_b64_v4i16((LAS s16x4*)(vp + (16 * s2) * VROW + 64 * d));
;                     const s16x4 hi = __builtin_amdgcn_ds_read_tr16_b64_v4i16((LAS s16x4*)(vp + (16 * s2 + 8) * VROW + 64 * d));
;                     const bf16x8 av = __builtin_shufflevector(lo, hi, 0, 1, 2, 3, 4, 5, 6, 7);
;                     O[d] = __builtin_amdgcn_mfma_f32_32x32x16_bf16(av, pb[s2], O[d], 0, 0, 0);
;                 }
;         }
;         __builtin_amdgcn_s_setprio(0);
.Lfast609:
	v_sub_f32_e32 v185, v64, v200
	v_exp_f32_e32 v185, v185
	v_sub_f32_e32 v64, v65, v200
	v_exp_f32_e32 v64, v64
	v_sub_f32_e32 v65, v66, v200
	v_exp_f32_e32 v65, v65
	v_sub_f32_e32 v66, v67, v200
	v_exp_f32_e32 v66, v66
	v_sub_f32_e32 v67, v68, v200
	v_exp_f32_e32 v67, v67
	v_sub_f32_e32 v68, v69, v200
	v_exp_f32_e32 v68, v68
	v_sub_f32_e32 v69, v70, v200
	v_exp_f32_e32 v69, v69
	v_sub_f32_e32 v70, v71, v200
	v_exp_f32_e32 v70, v70
	v_sub_f32_e32 v71, v72, v200
	v_exp_f32_e32 v71, v71
	v_sub_f32_e32 v72, v73, v200
	v_add_f32_e32 v187, 0, v185
	v_exp_f32_e32 v72, v72
	v_add_f32_e32 v187, v64, v187
	v_add_f32_e32 v187, v65, v187
	v_sub_f32_e32 v73, v74, v200
	v_add_f32_e32 v187, v66, v187
	v_exp_f32_e32 v73, v73
	v_sub_f32_e32 v74, v75, v200
	v_add_f32_e32 v187, v67, v187
	v_exp_f32_e32 v74, v74
	v_sub_f32_e32 v75, v76, v200
	v_add_f32_e32 v187, v68, v187
	v_exp_f32_e32 v75, v75
	v_add_f32_e32 v187, v69, v187
	v_add_f32_e32 v187, v70, v187
	v_sub_f32_e32 v76, v77, v200
	v_add_f32_e32 v187, v71, v187
	v_exp_f32_e32 v76, v76
	v_sub_f32_e32 v77, v78, v200
	v_add_f32_e32 v187, v72, v187
	v_exp_f32_e32 v77, v77
	v_sub_f32_e32 v78, v79, v200
	v_add_f32_e32 v187, v73, v187
	v_exp_f32_e32 v78, v78
	v_add_f32_e32 v187, v74, v187
	v_add_f32_e32 v187, v75, v187
	v_add_f32_e32 v187, v76, v187
	v_add_f32_e32 v187, v77, v187
	v_add_f32_e32 v79, v78, v187
	v_cvt_pk_bf16_f32 v64, v185, v64
	v_cvt_pk_bf16_f32 v65, v65, v66
	v_cvt_pk_bf16_f32 v66, v67, v68
	v_cvt_pk_bf16_f32 v67, v69, v70
	v_cvt_pk_bf16_f32 v68, v71, v72
	v_cvt_pk_bf16_f32 v69, v73, v74
	v_cvt_pk_bf16_f32 v70, v75, v76
	v_cvt_pk_bf16_f32 v71, v77, v78
	s_nop 0
	v_add_u32_e32 v72, s45, v201
	v_add3_u32 v78, v72, v225, v226
	ds_read_b64_tr_b16 v[72:73], v78 offset:25600
	ds_read_b64_tr_b16 v[74:75], v78 offset:28160
	ds_read_b64_tr_b16 v[76:77], v78 offset:33280
	ds_read_b64_tr_b16 v[206:207], v78 offset:25664
	ds_read_b64_tr_b16 v[210:211], v78 offset:25728
	ds_read_b64_tr_b16 v[214:215], v78 offset:25792
	ds_read_b64_tr_b16 v[208:209], v78 offset:28224
	ds_read_b64_tr_b16 v[212:213], v78 offset:28288
	ds_read_b64_tr_b16 v[216:217], v78 offset:28352
	s_waitcnt lgkmcnt(7)
	v_mfma_f32_32x32x16_bf16 v[48:63], v[72:75], v[64:67], v[48:63]
	ds_read_b64_tr_b16 v[74:75], v78 offset:30720
	ds_read_b64_tr_b16 v[232:233], v78 offset:30784
	ds_read_b64_tr_b16 v[236:237], v78 offset:30848
	ds_read_b64_tr_b16 v[240:241], v78 offset:30912
	ds_read_b64_tr_b16 v[234:235], v78 offset:33344
	ds_read_b64_tr_b16 v[238:239], v78 offset:33408
	ds_read_b64_tr_b16 v[242:243], v78 offset:33472
	v_add_f32_e32 v183, v183, v79
	s_waitcnt lgkmcnt(9)
	v_mfma_f32_32x32x16_bf16 v[32:47], v[206:209], v[64:67], v[32:47]
	s_waitcnt lgkmcnt(8)
	v_mfma_f32_32x32x16_bf16 v[16:31], v[210:213], v[64:67], v[16:31]
	s_waitcnt lgkmcnt(7)
	v_mfma_f32_32x32x16_bf16 v[0:15], v[214:217], v[64:67], v[0:15]
	s_waitcnt lgkmcnt(6)
	v_mfma_f32_32x32x16_bf16 v[48:63], v[74:77], v[68:71], v[48:63]
	s_waitcnt lgkmcnt(2)
	v_mfma_f32_32x32x16_bf16 v[32:47], v[232:235], v[68:71], v[32:47]
	s_waitcnt lgkmcnt(1)
	v_mfma_f32_32x32x16_bf16 v[16:31], v[236:239], v[68:71], v[16:31]
	s_waitcnt lgkmcnt(0)
	v_mfma_f32_32x32x16_bf16 v[0:15], v[240:243], v[68:71], v[0:15]
	s_nop 0
	s_add_i32 s43, s43, 64
	s_add_u32 s18, s18, 1
	s_addc_u32 s19, s19, 0
	v_lshl_add_u64 v[196:197], v[196:197], 0, s[10:11]
	s_cmp_eq_u32 s44, s43
	v_lshl_add_u64 v[198:199], v[198:199], 0, s[10:11]
	s_cbranch_scc1 .LBB0_616
	s_branch .LBB0_610
; #define LAS __attribute__((address_space(3)))
; DI unsigned pk2(float lo, float hi) { f32x2 v = {lo, hi}; bf2_t b = __builtin_convertvector(v, bf2_t); return __builtin_bit_cast(unsigned, b); }
; DI float fexp2(float x) { return __builtin_amdgcn_exp2f(x); }
; DI void attn_item(LAS unsigned char* lds, int bh, int qb, const bf16_t* QH, const bf16_t* KN, const bf16_t* KPE, const bf16_t* VT, const bf16_t* P, bf16_t* MIX) {
;     ...
;         float ps = 0.f;
; #pragma unroll
;         for (int i = 0; i < 16; ++i) { float p = fexp2(S[i] - mrow); if (diag && S[i] == NEG) p = 0.f; S[i] = p; ps += p; }
;         lrow += ps;
;         bf16x8 pb[2];
; #pragma unroll
;         for (int s2 = 0; s2 < 2; ++s2) { u32x4 w; w.x = pk2(S[8 * s2 + 0], S[8 * s2 + 1]); w.y = pk2(S[8 * s2 + 2], S[8 * s2 + 3]); w.z = pk2(S[8 * s2 + 4], S[8 * s2 + 5]); w.w = pk2(S[8 * s2 + 6], S[8 * s2 + 7]); pb[s2] = __builtin_bit_cast(bf16x8, w); }
;         __builtin_amdgcn_s_setprio(1);
;         {
;             const int li = lane & 15, gd = (lane >> 4) & 1;
;             const LAS unsigned char* vp = vb + (kh * 32 + 4 * h2 + (li >> 2)) * VROW + gd * 32 + (li & 3) * 8;
; #pragma unroll
;             for (int d = 0; d < 4; ++d)
; #pragma unroll
;                 for (int s2 = 0; s2 < 2; ++s2) {
;                     const s16x4 lo = __builtin_amdgcn_ds_read_tr16_b64_v4i16((LAS s16x4*)(vp + (16 * s2) * VROW + 64 * d));
;                     const s16x4 hi = __builtin_amdgcn_ds_read_tr16_b64_v4i16((LAS s16x4*)(vp + (16 * s2 + 8) * VROW + 64 * d));
;                     const bf16x8 av = __builtin_shufflevector(lo, hi, 0, 1, 2, 3, 4, 5, 6, 7);
;                     O[d] = __builtin_amdgcn_mfma_f32_32x32x16_bf16(av, pb[s2], O[d], 0, 0, 0);
;                 }
;         }
;         __builtin_amdgcn_s_setprio(0);
.LBB0_609:
	v_sub_f32_e32 v185, v64, v200
	v_exp_f32_e32 v185, v185
	v_cmp_eq_f32_e32 vcc, s30, v64
	v_sub_f32_e32 v64, v65, v200
	s_and_b64 s[46:47], s[20:21], vcc
	v_exp_f32_e32 v64, v64
	v_cmp_eq_f32_e32 vcc, s30, v65
	v_sub_f32_e32 v65, v66, v200
	v_cndmask_b32_e64 v185, v185, 0, s[46:47]
	s_and_b64 s[46:47], s[20:21], vcc
	v_exp_f32_e32 v65, v65
	v_cmp_eq_f32_e32 vcc, s30, v66
	v_sub_f32_e32 v66, v67, v200
	v_exp_f32_e32 v66, v66
	v_cndmask_b32_e64 v64, v64, 0, s[46:47]
	s_and_b64 s[46:47], s[20:21], vcc
	v_cmp_eq_f32_e32 vcc, s30, v67
	v_sub_f32_e32 v67, v68, v200
	v_cndmask_b32_e64 v65, v65, 0, s[46:47]
	s_and_b64 s[46:47], s[20:21], vcc
	v_exp_f32_e32 v67, v67
	v_cmp_eq_f32_e32 vcc, s30, v68
	v_sub_f32_e32 v68, v69, v200
	v_cndmask_b32_e64 v66, v66, 0, s[46:47]
	s_and_b64 s[46:47], s[20:21], vcc
	v_exp_f32_e32 v68, v68
	v_cmp_eq_f32_e32 vcc, s30, v69
	v_sub_f32_e32 v69, v70, v200
	v_exp_f32_e32 v69, v69
	v_cndmask_b32_e64 v67, v67, 0, s[46:47]
	s_and_b64 s[46:47], s[20:21], vcc
	v_cmp_eq_f32_e32 vcc, s30, v70
	v_sub_f32_e32 v70, v71, v200
	v_cndmask_b32_e64 v68, v68, 0, s[46:47]
	s_and_b64 s[46:47], s[20:21], vcc
	v_exp_f32_e32 v70, v70
	v_cmp_eq_f32_e32 vcc, s30, v71
	v_sub_f32_e32 v71, v72, v200
	v_cndmask_b32_e64 v69, v69, 0, s[46:47]
	s_and_b64 s[46:47], s[20:21], vcc
	v_exp_f32_e32 v71, v71
	v_cmp_eq_f32_e32 vcc, s30, v72
	v_sub_f32_e32 v72, v73, v200
	v_add_f32_e32 v187, 0, v185
	v_exp_f32_e32 v72, v72
	v_add_f32_e32 v187, v64, v187
	v_add_f32_e32 v187, v65, v187
	v_cndmask_b32_e64 v70, v70, 0, s[46:47]
	s_and_b64 s[46:47], s[20:21], vcc
	v_cmp_eq_f32_e32 vcc, s30, v73
	v_sub_f32_e32 v73, v74, v200
	v_add_f32_e32 v187, v66, v187
	v_cndmask_b32_e64 v71, v71, 0, s[46:47]
	s_and_b64 s[46:47], s[20:21], vcc
	v_exp_f32_e32 v73, v73
	v_cmp_eq_f32_e32 vcc, s30, v74
	v_sub_f32_e32 v74, v75, v200
	v_add_f32_e32 v187, v67, v187
	v_cndmask_b32_e64 v72, v72, 0, s[46:47]
	s_and_b64 s[46:47], s[20:21], vcc
	v_exp_f32_e32 v74, v74
	v_cmp_eq_f32_e32 vcc, s30, v75
	v_sub_f32_e32 v75, v76, v200
	v_add_f32_e32 v187, v68, v187
	v_exp_f32_e32 v75, v75
	v_add_f32_e32 v187, v69, v187
	v_add_f32_e32 v187, v70, v187
	v_cndmask_b32_e64 v73, v73, 0, s[46:47]
	s_and_b64 s[46:47], s[20:21], vcc
	v_cmp_eq_f32_e32 vcc, s30, v76
	v_sub_f32_e32 v76, v77, v200
	v_add_f32_e32 v187, v71, v187
	v_cndmask_b32_e64 v74, v74, 0, s[46:47]
	s_and_b64 s[46:47], s[20:21], vcc
	v_exp_f32_e32 v76, v76
	v_cmp_eq_f32_e32 vcc, s30, v77
	v_sub_f32_e32 v77, v78, v200
	v_add_f32_e32 v187, v72, v187
	v_cndmask_b32_e64 v75, v75, 0, s[46:47]
	s_and_b64 s[46:47], s[20:21], vcc
	v_exp_f32_e32 v77, v77
	v_cmp_eq_f32_e32 vcc, s30, v78
	v_sub_f32_e32 v78, v79, v200
	v_add_f32_e32 v187, v73, v187
	v_exp_f32_e32 v78, v78
	v_add_f32_e32 v187, v74, v187
	v_add_f32_e32 v187, v75, v187
	v_cndmask_b32_e64 v76, v76, 0, s[46:47]
	s_and_b64 s[46:47], s[20:21], vcc
	v_cmp_eq_f32_e32 vcc, s30, v79
	v_add_f32_e32 v187, v76, v187
	v_cndmask_b32_e64 v77, v77, 0, s[46:47]
	s_and_b64 s[20:21], s[20:21], vcc
	v_add_f32_e32 v187, v77, v187
	v_cndmask_b32_e64 v78, v78, 0, s[20:21]
	v_add_f32_e32 v79, v78, v187
	v_cvt_pk_bf16_f32 v64, v185, v64
	v_cvt_pk_bf16_f32 v65, v65, v66
	v_cvt_pk_bf16_f32 v66, v67, v68
	v_cvt_pk_bf16_f32 v67, v69, v70
	v_cvt_pk_bf16_f32 v68, v71, v72
	v_cvt_pk_bf16_f32 v69, v73, v74
	v_cvt_pk_bf16_f32 v70, v75, v76
	v_cvt_pk_bf16_f32 v71, v77, v78
	s_nop 0
	v_add_u32_e32 v72, s45, v201
	v_add3_u32 v78, v72, v225, v226
	ds_read_b64_tr_b16 v[72:73], v78 offset:25600
	ds_read_b64_tr_b16 v[74:75], v78 offset:28160
	ds_read_b64_tr_b16 v[76:77], v78 offset:33280
	ds_read_b64_tr_b16 v[206:207], v78 offset:25664
	ds_read_b64_tr_b16 v[210:211], v78 offset:25728
	ds_read_b64_tr_b16 v[214:215], v78 offset:25792
	ds_read_b64_tr_b16 v[208:209], v78 offset:28224
	ds_read_b64_tr_b16 v[212:213], v78 offset:28288
	ds_read_b64_tr_b16 v[216:217], v78 offset:28352
	s_waitcnt lgkmcnt(7)
	v_mfma_f32_32x32x16_bf16 v[48:63], v[72:75], v[64:67], v[48:63]
	ds_read_b64_tr_b16 v[74:75], v78 offset:30720
	ds_read_b64_tr_b16 v[232:233], v78 offset:30784
	ds_read_b64_tr_b16 v[236:237], v78 offset:30848
	ds_read_b64_tr_b16 v[240:241], v78 offset:30912
	ds_read_b64_tr_b16 v[234:235], v78 offset:33344
	ds_read_b64_tr_b16 v[238:239], v78 offset:33408
	ds_read_b64_tr_b16 v[242:243], v78 offset:33472
	v_add_f32_e32 v183, v183, v79
	s_waitcnt lgkmcnt(9)
	v_mfma_f32_32x32x16_bf16 v[32:47], v[206:209], v[64:67], v[32:47]
	s_waitcnt lgkmcnt(8)
	v_mfma_f32_32x32x16_bf16 v[16:31], v[210:213], v[64:67], v[16:31]
	s_waitcnt lgkmcnt(7)
	v_mfma_f32_32x32x16_bf16 v[0:15], v[214:217], v[64:67], v[0:15]
	s_waitcnt lgkmcnt(6)
	v_mfma_f32_32x32x16_bf16 v[48:63], v[74:77], v[68:71], v[48:63]
	s_waitcnt lgkmcnt(2)
	v_mfma_f32_32x32x16_bf16 v[32:47], v[232:235], v[68:71], v[32:47]
	s_waitcnt lgkmcnt(1)
	v_mfma_f32_32x32x16_bf16 v[16:31], v[236:239], v[68:71], v[16:31]
	s_waitcnt lgkmcnt(0)
	v_mfma_f32_32x32x16_bf16 v[0:15], v[240:243], v[68:71], v[0:15]
	s_nop 0
	s_add_i32 s43, s43, 64
	s_add_u32 s18, s18, 1
	s_addc_u32 s19, s19, 0
	v_lshl_add_u64 v[196:197], v[196:197], 0, s[10:11]
	s_cmp_eq_u32 s44, s43
	v_lshl_add_u64 v[198:199], v[198:199], 0, s[10:11]
	s_cbranch_scc1 .LBB0_616

; #define LAS __attribute__((address_space(3)))
; DI void attn_item(LAS unsigned char* lds, int bh, int qb, const bf16_t* QH, const bf16_t* KN, const bf16_t* KPE, const bf16_t* VT, const bf16_t* P, bf16_t* MIX) {
;     ...
;         { const LAS unsigned char* kp = kb + (kh * 32 + r) * KROW + 16 * h2;
;           __builtin_amdgcn_s_setprio(1);
; #pragma unroll
;           for (int ks = 0; ks < 12; ++ks) { const bf16x8 a = *(const LAS bf16x8*)(kp + 32 * ks); S = __builtin_amdgcn_mfma_f32_32x32x16_bf16(a, Qf[ks], S, 0, 0, 0); }
;           __builtin_amdgcn_sched_group_barrier(0x100, 4, 0);
; #pragma unroll
;           for (int i = 0; i < 8; ++i) { __builtin_amdgcn_sched_group_barrier(0x008, 1, 0); __builtin_amdgcn_sched_group_barrier(0x100, 1, 0); }
;           __builtin_amdgcn_sched_group_barrier(0x008, 4, 0);
;           __builtin_amdgcn_s_setprio(0); }
;         const bool diag = (t >= 2 * qb);
;         if (diag) {
;             const int key0 = t * 64 + kh * 32 + 4 * h2;
; #pragma unroll
;             for (int i = 0; i < 16; ++i) { const int key = key0 + (i & 3) + 8 * (i >> 2); if (key > qpos) S[i] = NEG; }
.LBB0_612:
	s_bitcmp1_b32 s46, 0
	s_cselect_b32 s20, 0xb400, 0
	s_add_i32 s45, s20, 0
	v_add3_u32 v185, s45, v205, v164
	s_nop 0
	ds_read_b128 v[64:67], v185
	ds_read_b128 v[206:209], v185 offset:32
	ds_read_b128 v[210:213], v185 offset:64
	ds_read_b128 v[214:217], v185 offset:96
	s_waitcnt lgkmcnt(3)
	v_mfma_f32_32x32x16_bf16 v[64:79], v[64:67], v[124:127], 0
	ds_read_b128 v[232:235], v185 offset:128
	s_waitcnt lgkmcnt(3)
	v_mfma_f32_32x32x16_bf16 v[64:79], v[206:209], v[120:123], v[64:79]
	ds_read_b128 v[206:209], v185 offset:160
	s_waitcnt lgkmcnt(3)
	v_mfma_f32_32x32x16_bf16 v[64:79], v[210:213], v[116:119], v[64:79]
	ds_read_b128 v[210:213], v185 offset:192
	s_waitcnt lgkmcnt(3)
	v_mfma_f32_32x32x16_bf16 v[64:79], v[214:217], v[112:115], v[64:79]
	ds_read_b128 v[214:217], v185 offset:224
	s_waitcnt lgkmcnt(3)
	v_mfma_f32_32x32x16_bf16 v[64:79], v[232:235], v[104:107], v[64:79]
	ds_read_b128 v[232:235], v185 offset:256
	s_waitcnt lgkmcnt(3)
	v_mfma_f32_32x32x16_bf16 v[64:79], v[206:209], v[96:99], v[64:79]
	ds_read_b128 v[206:209], v185 offset:288
	s_waitcnt lgkmcnt(3)
	v_mfma_f32_32x32x16_bf16 v[64:79], v[210:213], v[92:95], v[64:79]
	ds_read_b128 v[210:213], v185 offset:320
	s_waitcnt lgkmcnt(3)
	v_mfma_f32_32x32x16_bf16 v[64:79], v[214:217], v[88:91], v[64:79]
	ds_read_b128 v[214:217], v185 offset:352
	s_waitcnt lgkmcnt(3)
	v_mfma_f32_32x32x16_bf16 v[64:79], v[232:235], v[80:83], v[64:79]
	s_waitcnt lgkmcnt(2)
	v_mfma_f32_32x32x16_bf16 v[64:79], v[206:209], v[84:87], v[64:79]
	s_waitcnt lgkmcnt(1)
	v_mfma_f32_32x32x16_bf16 v[64:79], v[210:213], v[108:111], v[64:79]
	s_waitcnt lgkmcnt(0)
	v_mfma_f32_32x32x16_bf16 v[64:79], v[214:217], v[100:103], v[64:79]
	s_nop 0
	s_cmp_ge_u32 s46, s42
	s_cselect_b64 s[20:21], -1, 0
	s_cmp_lt_u32 s46, s42
	s_cbranch_scc1 .LBB0_614
	v_add_u32_e32 v185, s43, v204
	v_cmp_lt_u32_e32 vcc, v185, v203
	v_add_u32_e32 v187, 2, v185
	s_nop 3
	v_cndmask_b32_e32 v65, v230, v65, vcc
	v_cmp_le_u32_e32 vcc, v185, v203
	s_nop 1
	v_cndmask_b32_e32 v64, v230, v64, vcc
	v_cmp_le_u32_e32 vcc, v187, v203
	v_add_u32_e32 v187, 3, v185
	s_nop 0
	v_cndmask_b32_e32 v66, v230, v66, vcc
	v_cmp_le_u32_e32 vcc, v187, v203
	v_add_u32_e32 v187, 8, v185
	s_nop 0
	v_cndmask_b32_e32 v67, v230, v67, vcc
	v_cmp_le_u32_e32 vcc, v187, v203
	v_add_u32_e32 v187, 9, v185
	s_nop 0
	v_cndmask_b32_e32 v68, v230, v68, vcc
	v_cmp_le_u32_e32 vcc, v187, v203
	v_add_u32_e32 v187, 10, v185
	s_nop 0
	v_cndmask_b32_e32 v69, v230, v69, vcc
	v_cmp_le_u32_e32 vcc, v187, v203
	v_add_u32_e32 v187, 11, v185
	s_nop 0
	v_cndmask_b32_e32 v70, v230, v70, vcc
	v_cmp_le_u32_e32 vcc, v187, v203
	v_add_u32_e32 v187, 16, v185
	s_nop 0
	v_cndmask_b32_e32 v71, v230, v71, vcc
	v_cmp_le_u32_e32 vcc, v187, v203
	v_add_u32_e32 v187, 17, v185
	s_nop 0
	v_cndmask_b32_e32 v72, v230, v72, vcc
	v_cmp_le_u32_e32 vcc, v187, v203
	v_add_u32_e32 v187, 18, v185
	s_nop 0
	v_cndmask_b32_e32 v73, v230, v73, vcc
	v_cmp_le_u32_e32 vcc, v187, v203
	v_add_u32_e32 v187, 19, v185
	s_nop 0
	v_cndmask_b32_e32 v74, v230, v74, vcc
	v_cmp_le_u32_e32 vcc, v187, v203
	v_add_u32_e32 v187, 24, v185
	s_nop 0
	v_cndmask_b32_e32 v75, v230, v75, vcc
	v_cmp_le_u32_e32 vcc, v187, v203
	v_add_u32_e32 v187, 25, v185
	s_nop 0
	v_cndmask_b32_e32 v76, v230, v76, vcc
	v_cmp_le_u32_e32 vcc, v187, v203
	v_add_u32_e32 v187, 26, v185
	v_add_u32_e32 v185, 27, v185
	v_cndmask_b32_e32 v77, v230, v77, vcc
	v_cmp_le_u32_e32 vcc, v187, v203
	s_nop 1
	v_cndmask_b32_e32 v78, v230, v78, vcc
	v_cmp_le_u32_e32 vcc, v185, v203
	s_nop 1
	v_cndmask_b32_e32 v79, v230, v79, vcc

; #define LAS __attribute__((address_space(3)))
; DI float fexp2(float x) { return __builtin_amdgcn_exp2f(x); }
; DI void attn_item(LAS unsigned char* lds, int bh, int qb, const bf16_t* QH, const bf16_t* KN, const bf16_t* KPE, const bf16_t* VT, const bf16_t* P, bf16_t* MIX) {
;     ...
;         { const LAS unsigned char* kp = kb + (kh * 32 + r) * KROW + 16 * h2;
;           __builtin_amdgcn_s_setprio(1);
; #pragma unroll
;           for (int ks = 0; ks < 12; ++ks) { const bf16x8 a = *(const LAS bf16x8*)(kp + 32 * ks); S = __builtin_amdgcn_mfma_f32_32x32x16_bf16(a, Qf[ks], S, 0, 0, 0); }
;           __builtin_amdgcn_sched_group_barrier(0x100, 4, 0);
; #pragma unroll
;           for (int i = 0; i < 8; ++i) { __builtin_amdgcn_sched_group_barrier(0x008, 1, 0); __builtin_amdgcn_sched_group_barrier(0x100, 1, 0); }
;           __builtin_amdgcn_sched_group_barrier(0x008, 4, 0);
;           __builtin_amdgcn_s_setprio(0); }
;         const bool diag = (t >= 2 * qb);
;         if (diag) {
;             const int key0 = t * 64 + kh * 32 + 4 * h2;
; #pragma unroll
;             for (int i = 0; i < 16; ++i) { const int key = key0 + (i & 3) + 8 * (i >> 2); if (key > qpos) S[i] = NEG; }
;         }
;         float mx = S[0];
; #pragma unroll
;         for (int i = 1; i < 16; ++i) mx = fmaxf(mx, S[i]);
;         mx = fmaxf(mx, __shfl_xor(mx, 32));
;         if (__any(mx > mrow + 8.f)) {
;             const float mnew = fmaxf(mrow, mx);
;             const float alpha = fexp2(mrow - mnew);
;             mrow = mnew; lrow *= alpha;
; #pragma unroll
;             for (int d = 0; d < 4; ++d)
; #pragma unroll
;                 for (int i = 0; i < 16; ++i) O[d][i] *= alpha;
;         }
.LBB0_616:
	s_lshl_b32 s18, s18, 6
	s_barrier
	v_add3_u32 v140, s41, v205, v164
	s_nop 0
	ds_read_b128 v[64:67], v140
	ds_read_b128 v[128:131], v140 offset:32
	ds_read_b128 v[132:135], v140 offset:64
	ds_read_b128 v[136:139], v140 offset:96
	s_waitcnt lgkmcnt(3)
	v_mfma_f32_32x32x16_bf16 v[64:79], v[64:67], v[124:127], 0
	ds_read_b128 v[124:127], v140 offset:128
	s_waitcnt lgkmcnt(3)
	v_mfma_f32_32x32x16_bf16 v[64:79], v[128:131], v[120:123], v[64:79]
	ds_read_b128 v[120:123], v140 offset:160
	s_waitcnt lgkmcnt(3)
	v_mfma_f32_32x32x16_bf16 v[64:79], v[132:135], v[116:119], v[64:79]
	ds_read_b128 v[116:119], v140 offset:192
	s_waitcnt lgkmcnt(3)
	v_mfma_f32_32x32x16_bf16 v[64:79], v[136:139], v[112:115], v[64:79]
	ds_read_b128 v[112:115], v140 offset:224
	s_waitcnt lgkmcnt(3)
	v_mfma_f32_32x32x16_bf16 v[64:79], v[124:127], v[104:107], v[64:79]
	ds_read_b128 v[104:107], v140 offset:256
	s_waitcnt lgkmcnt(3)
	v_mfma_f32_32x32x16_bf16 v[64:79], v[120:123], v[96:99], v[64:79]
	ds_read_b128 v[96:99], v140 offset:288
	s_waitcnt lgkmcnt(3)
	v_mfma_f32_32x32x16_bf16 v[64:79], v[116:119], v[92:95], v[64:79]
	ds_read_b128 v[92:95], v140 offset:320
	s_waitcnt lgkmcnt(3)
	v_mfma_f32_32x32x16_bf16 v[64:79], v[112:115], v[88:91], v[64:79]
	ds_read_b128 v[88:91], v140 offset:352
	s_waitcnt lgkmcnt(3)
	v_mfma_f32_32x32x16_bf16 v[64:79], v[104:107], v[80:83], v[64:79]
	s_waitcnt lgkmcnt(2)
	v_mfma_f32_32x32x16_bf16 v[64:79], v[96:99], v[84:87], v[64:79]
	s_waitcnt lgkmcnt(1)
	v_mfma_f32_32x32x16_bf16 v[64:79], v[92:95], v[108:111], v[64:79]
	s_waitcnt lgkmcnt(0)
	v_mfma_f32_32x32x16_bf16 v[64:79], v[88:91], v[100:103], v[64:79]
	s_nop 0
	s_addk_i32 s18, 0xff80
	v_add_u32_e32 v88, s18, v204
	v_cmp_le_u32_e32 vcc, v88, v203
	s_nop 7
	v_cndmask_b32_e32 v87, v230, v64, vcc
	v_cmp_lt_u32_e32 vcc, v88, v203
	v_or_b32_e32 v64, 2, v88
	s_nop 0
	v_cndmask_b32_e32 v86, v230, v65, vcc
	v_cmp_le_u32_e32 vcc, v64, v203
	v_or_b32_e32 v64, 3, v88
	v_or_b32_e32 v65, 27, v88
	v_cndmask_b32_e32 v84, v230, v66, vcc
	v_cmp_le_u32_e32 vcc, v64, v203
	v_or_b32_e32 v64, 8, v88
	s_nop 0
	v_cndmask_b32_e32 v85, v230, v67, vcc
	v_cmp_le_u32_e32 vcc, v64, v203
	v_or_b32_e32 v64, 9, v88
	s_nop 0
	v_cndmask_b32_e32 v82, v230, v68, vcc
	v_cmp_le_u32_e32 vcc, v64, v203
	v_or_b32_e32 v64, 10, v88
	s_nop 0
	v_cndmask_b32_e32 v83, v230, v69, vcc
	v_cmp_le_u32_e32 vcc, v64, v203
	v_or_b32_e32 v64, 11, v88
	s_nop 0
	v_cndmask_b32_e32 v80, v230, v70, vcc
	v_cmp_le_u32_e32 vcc, v64, v203
	v_or_b32_e32 v64, 16, v88
	s_nop 0
	v_cndmask_b32_e32 v81, v230, v71, vcc
	v_cmp_le_u32_e32 vcc, v64, v203
	v_or_b32_e32 v64, 17, v88
	s_nop 0
	v_cndmask_b32_e32 v70, v230, v72, vcc
	v_cmp_le_u32_e32 vcc, v64, v203
	v_or_b32_e32 v64, 18, v88
	v_max_f32_e32 v72, v86, v86
	v_cndmask_b32_e32 v71, v230, v73, vcc
	v_max_f32_e32 v73, v87, v87
	v_cmp_le_u32_e32 vcc, v64, v203
	v_or_b32_e32 v64, 19, v88
	v_max_f32_e32 v72, v73, v72
	v_cndmask_b32_e32 v68, v230, v74, vcc
	v_cmp_le_u32_e32 vcc, v64, v203
	v_or_b32_e32 v64, 24, v88
	v_max3_f32 v72, v72, v84, v85
	v_cndmask_b32_e32 v69, v230, v75, vcc
	v_cmp_le_u32_e32 vcc, v64, v203
	v_or_b32_e32 v64, 25, v88
	v_max3_f32 v72, v72, v82, v83
	v_cndmask_b32_e32 v66, v230, v76, vcc
	v_cmp_le_u32_e32 vcc, v64, v203
	v_or_b32_e32 v64, 26, v88
	v_max3_f32 v72, v72, v80, v81
	v_cndmask_b32_e32 v67, v230, v77, vcc
	v_cmp_le_u32_e32 vcc, v64, v203
	v_max3_f32 v72, v72, v70, v71
	v_max3_f32 v72, v72, v68, v69
	v_cndmask_b32_e32 v64, v230, v78, vcc
	v_cmp_le_u32_e32 vcc, v65, v203
	v_max3_f32 v72, v72, v66, v67
	s_nop 0
	v_cndmask_b32_e32 v65, v230, v79, vcc
	v_max3_f32 v72, v72, v64, v65
	ds_bpermute_b32 v73, v165, v72
	s_waitcnt lgkmcnt(0)
	v_max_f32_e32 v73, v73, v73
	v_max_f32_e32 v72, v72, v73
	v_add_f32_e32 v73, 0x41000000, v200
	v_cmp_gt_f32_e32 vcc, v72, v73
	s_cbranch_vccz .LBB0_618
	v_max_f32_e32 v72, v72, v72
	v_max_f32_e32 v73, v200, v200
	v_max_f32_e32 v73, v73, v72
	v_sub_f32_e32 v72, v200, v73
	v_exp_f32_e32 v72, v72
	v_mov_b32_e32 v200, v73
	v_pk_mul_f32 v[62:63], v[62:63], v[72:73] op_sel_hi:[1,0]
	v_pk_mul_f32 v[60:61], v[60:61], v[72:73] op_sel_hi:[1,0]
	v_pk_mul_f32 v[58:59], v[58:59], v[72:73] op_sel_hi:[1,0]
	v_pk_mul_f32 v[56:57], v[56:57], v[72:73] op_sel_hi:[1,0]
	v_pk_mul_f32 v[54:55], v[54:55], v[72:73] op_sel_hi:[1,0]
	v_pk_mul_f32 v[52:53], v[52:53], v[72:73] op_sel_hi:[1,0]
	v_pk_mul_f32 v[50:51], v[50:51], v[72:73] op_sel_hi:[1,0]
	v_pk_mul_f32 v[48:49], v[48:49], v[72:73] op_sel_hi:[1,0]
	v_pk_mul_f32 v[46:47], v[46:47], v[72:73] op_sel_hi:[1,0]
	v_pk_mul_f32 v[44:45], v[44:45], v[72:73] op_sel_hi:[1,0]
	v_pk_mul_f32 v[42:43], v[42:43], v[72:73] op_sel_hi:[1,0]
	v_pk_mul_f32 v[40:41], v[40:41], v[72:73] op_sel_hi:[1,0]
	v_pk_mul_f32 v[38:39], v[38:39], v[72:73] op_sel_hi:[1,0]
	v_pk_mul_f32 v[36:37], v[36:37], v[72:73] op_sel_hi:[1,0]
	v_pk_mul_f32 v[34:35], v[34:35], v[72:73] op_sel_hi:[1,0]
	v_pk_mul_f32 v[32:33], v[32:33], v[72:73] op_sel_hi:[1,0]
	v_pk_mul_f32 v[30:31], v[30:31], v[72:73] op_sel_hi:[1,0]
	v_pk_mul_f32 v[28:29], v[28:29], v[72:73] op_sel_hi:[1,0]
	v_pk_mul_f32 v[26:27], v[26:27], v[72:73] op_sel_hi:[1,0]
	v_pk_mul_f32 v[24:25], v[24:25], v[72:73] op_sel_hi:[1,0]
	v_pk_mul_f32 v[22:23], v[22:23], v[72:73] op_sel_hi:[1,0]
	v_pk_mul_f32 v[20:21], v[20:21], v[72:73] op_sel_hi:[1,0]
	v_pk_mul_f32 v[18:19], v[18:19], v[72:73] op_sel_hi:[1,0]
	v_pk_mul_f32 v[16:17], v[16:17], v[72:73] op_sel_hi:[1,0]
	v_pk_mul_f32 v[14:15], v[14:15], v[72:73] op_sel_hi:[1,0]
	v_pk_mul_f32 v[12:13], v[12:13], v[72:73] op_sel_hi:[1,0]
	v_pk_mul_f32 v[10:11], v[10:11], v[72:73] op_sel_hi:[1,0]
	v_pk_mul_f32 v[8:9], v[8:9], v[72:73] op_sel_hi:[1,0]
	v_pk_mul_f32 v[6:7], v[6:7], v[72:73] op_sel_hi:[1,0]
	v_pk_mul_f32 v[4:5], v[4:5], v[72:73] op_sel_hi:[1,0]
	v_pk_mul_f32 v[2:3], v[2:3], v[72:73] op_sel_hi:[1,0]
	v_pk_mul_f32 v[0:1], v[0:1], v[72:73] op_sel_hi:[1,0]
	v_mul_f32_e32 v183, v183, v72
; #define LAS __attribute__((address_space(3)))
; DI unsigned pk2(float lo, float hi) { f32x2 v = {lo, hi}; bf2_t b = __builtin_convertvector(v, bf2_t); return __builtin_bit_cast(unsigned, b); }
; DI float fexp2(float x) { return __builtin_amdgcn_exp2f(x); }
; DI void attn_item(LAS unsigned char* lds, int bh, int qb, const bf16_t* QH, const bf16_t* KN, const bf16_t* KPE, const bf16_t* VT, const bf16_t* P, bf16_t* MIX) {
;     ...
;         float ps = 0.f;
; #pragma unroll
;         for (int i = 0; i < 16; ++i) { float p = fexp2(S[i] - mrow); if (diag && S[i] == NEG) p = 0.f; S[i] = p; ps += p; }
;         lrow += ps;
;         bf16x8 pb[2];
; #pragma unroll
;         for (int s2 = 0; s2 < 2; ++s2) { u32x4 w; w.x = pk2(S[8 * s2 + 0], S[8 * s2 + 1]); w.y = pk2(S[8 * s2 + 2], S[8 * s2 + 3]); w.z = pk2(S[8 * s2 + 4], S[8 * s2 + 5]); w.w = pk2(S[8 * s2 + 6], S[8 * s2 + 7]); pb[s2] = __builtin_bit_cast(bf16x8, w); }
;         __builtin_amdgcn_s_setprio(1);
;         {
;             const int li = lane & 15, gd = (lane >> 4) & 1;
;             const LAS unsigned char* vp = vb + (kh * 32 + 4 * h2 + (li >> 2)) * VROW + gd * 32 + (li & 3) * 8;
; #pragma unroll
;             for (int d = 0; d < 4; ++d)
; #pragma unroll
;                 for (int s2 = 0; s2 < 2; ++s2) {
;                     const s16x4 lo = __builtin_amdgcn_ds_read_tr16_b64_v4i16((LAS s16x4*)(vp + (16 * s2) * VROW + 64 * d));
;                     const s16x4 hi = __builtin_amdgcn_ds_read_tr16_b64_v4i16((LAS s16x4*)(vp + (16 * s2 + 8) * VROW + 64 * d));
;                     const bf16x8 av = __builtin_shufflevector(lo, hi, 0, 1, 2, 3, 4, 5, 6, 7);
;                     O[d] = __builtin_amdgcn_mfma_f32_32x32x16_bf16(av, pb[s2], O[d], 0, 0, 0);
;                 }
;         }
;         __builtin_amdgcn_s_setprio(0);
;     }
;     __syncthreads();
;     ...
;     lrow += __shfl_xor(lrow, 32);
;     LAS float* mb = (LAS float*)lds + (rg * 64 + lane) * 66;
;     if (kh == 1) {
; #pragma unroll
;         for (int d = 0; d < 4; ++d)
; #pragma unroll
;             for (int i = 0; i < 16; ++i) mb[d * 16 + i] = O[d][i];
;         mb[64] = mrow; mb[65] = lrow;
.LBB0_618:
	v_sub_f32_e32 v72, v87, v200
	v_exp_f32_e32 v72, v72
	v_sub_f32_e32 v73, v86, v200
	v_exp_f32_e32 v73, v73
	v_sub_f32_e32 v75, v84, v200
	v_exp_f32_e32 v75, v75
	v_sub_f32_e32 v76, v85, v200
	v_cmp_neq_f32_e32 vcc, s30, v87
	v_exp_f32_e32 v76, v76
	v_sub_f32_e32 v77, v82, v200
	v_cndmask_b32_e32 v72, 0, v72, vcc
	v_cmp_neq_f32_e32 vcc, s30, v86
	v_exp_f32_e32 v77, v77
	v_sub_f32_e32 v78, v83, v200
	v_cndmask_b32_e32 v73, 0, v73, vcc
	v_cmp_neq_f32_e32 vcc, s30, v84
	v_exp_f32_e32 v78, v78
	v_sub_f32_e32 v79, v80, v200
	v_cndmask_b32_e32 v75, 0, v75, vcc
	v_cmp_neq_f32_e32 vcc, s30, v85
	v_exp_f32_e32 v79, v79
	v_add_f32_e32 v74, 0, v72
	v_cndmask_b32_e32 v76, 0, v76, vcc
	v_cmp_neq_f32_e32 vcc, s30, v82
	v_sub_f32_e32 v82, v81, v200
	v_exp_f32_e32 v82, v82
	v_cndmask_b32_e32 v77, 0, v77, vcc
	v_cmp_neq_f32_e32 vcc, s30, v83
	v_add_f32_e32 v74, v73, v74
	v_add_f32_e32 v74, v75, v74
	v_cndmask_b32_e32 v78, 0, v78, vcc
	v_cmp_neq_f32_e32 vcc, s30, v80
	v_add_f32_e32 v74, v76, v74
	v_add_f32_e32 v74, v77, v74
	v_cndmask_b32_e32 v79, 0, v79, vcc
	v_cmp_neq_f32_e32 vcc, s30, v81
	v_sub_f32_e32 v81, v70, v200
	v_exp_f32_e32 v81, v81
	v_cndmask_b32_e32 v80, 0, v82, vcc
	v_sub_f32_e32 v82, v71, v200
	v_cmp_neq_f32_e32 vcc, s30, v70
	v_exp_f32_e32 v82, v82
	v_add_f32_e32 v74, v78, v74
	v_cndmask_b32_e32 v70, 0, v81, vcc
	v_sub_f32_e32 v81, v68, v200
	v_exp_f32_e32 v81, v81
	v_add_f32_e32 v74, v79, v74
	v_add_f32_e32 v74, v80, v74
	v_cmp_neq_f32_e32 vcc, s30, v71
	v_add_f32_e32 v74, v70, v74
	s_nop 0
	v_cndmask_b32_e32 v71, 0, v82, vcc
	v_cmp_neq_f32_e32 vcc, s30, v68
	v_add_f32_e32 v74, v71, v74
	v_sub_f32_e32 v82, v69, v200
	v_cndmask_b32_e32 v81, 0, v81, vcc
	v_exp_f32_e32 v82, v82
	v_add_f32_e32 v68, v81, v74
	v_sub_f32_e32 v74, v66, v200
	v_exp_f32_e32 v74, v74
	v_cmp_neq_f32_e32 vcc, s30, v69
	s_nop 1
	v_cndmask_b32_e32 v69, 0, v82, vcc
	v_sub_f32_e32 v82, v67, v200
	v_cmp_neq_f32_e32 vcc, s30, v66
	v_add_f32_e32 v68, v69, v68
	v_exp_f32_e32 v82, v82
	v_cndmask_b32_e32 v74, 0, v74, vcc
	v_cmp_neq_f32_e32 vcc, s30, v67
	v_sub_f32_e32 v67, v64, v200
	v_add_f32_e32 v66, v74, v68
	v_exp_f32_e32 v67, v67
	v_sub_f32_e32 v68, v65, v200
	v_exp_f32_e32 v68, v68
	v_cndmask_b32_e32 v82, 0, v82, vcc
	v_cmp_neq_f32_e32 vcc, s30, v64
	v_add_f32_e32 v66, v82, v66
	v_cvt_pk_bf16_f32 v69, v81, v69
	v_cndmask_b32_e32 v83, 0, v67, vcc
	v_cmp_neq_f32_e32 vcc, s30, v65
	v_add_f32_e32 v64, v83, v66
	v_cvt_pk_bf16_f32 v67, v79, v80
	v_cndmask_b32_e32 v84, 0, v68, vcc
	v_add_f32_e32 v102, v84, v64
	v_cvt_pk_bf16_f32 v64, v72, v73
	v_cvt_pk_bf16_f32 v65, v75, v76
	v_cvt_pk_bf16_f32 v66, v77, v78
	v_cvt_pk_bf16_f32 v68, v70, v71
	v_cvt_pk_bf16_f32 v70, v74, v82
	v_cvt_pk_bf16_f32 v71, v83, v84
	s_nop 0
	v_add_u32_e32 v72, s41, v201
	v_add3_u32 v100, v72, v225, v226
	ds_read_b64_tr_b16 v[72:73], v100 offset:25600
	ds_read_b64_tr_b16 v[74:75], v100 offset:28160
	ds_read_b64_tr_b16 v[76:77], v100 offset:33280
	ds_read_b64_tr_b16 v[78:79], v100 offset:25664
	ds_read_b64_tr_b16 v[82:83], v100 offset:25728
	ds_read_b64_tr_b16 v[86:87], v100 offset:25792
	ds_read_b64_tr_b16 v[80:81], v100 offset:28224
	ds_read_b64_tr_b16 v[84:85], v100 offset:28288
	ds_read_b64_tr_b16 v[88:89], v100 offset:28352
	s_waitcnt lgkmcnt(7)
	v_mfma_f32_32x32x16_bf16 v[48:63], v[72:75], v[64:67], v[48:63]
	ds_read_b64_tr_b16 v[74:75], v100 offset:30720
	ds_read_b64_tr_b16 v[90:91], v100 offset:30784
	ds_read_b64_tr_b16 v[94:95], v100 offset:30848
	ds_read_b64_tr_b16 v[98:99], v100 offset:30912
	ds_read_b64_tr_b16 v[92:93], v100 offset:33344
	ds_read_b64_tr_b16 v[96:97], v100 offset:33408
	ds_read_b64_tr_b16 v[100:101], v100 offset:33472
	s_waitcnt lgkmcnt(9)
	v_mfma_f32_32x32x16_bf16 v[32:47], v[78:81], v[64:67], v[32:47]
	s_waitcnt lgkmcnt(8)
	v_mfma_f32_32x32x16_bf16 v[16:31], v[82:85], v[64:67], v[16:31]
	s_waitcnt lgkmcnt(7)
	v_mfma_f32_32x32x16_bf16 v[0:15], v[86:89], v[64:67], v[0:15]
	v_add_f32_e32 v64, v183, v102
	s_waitcnt lgkmcnt(6)
	v_mfma_f32_32x32x16_bf16 v[48:63], v[74:77], v[68:71], v[48:63]
	s_waitcnt lgkmcnt(2)
	v_mfma_f32_32x32x16_bf16 v[32:47], v[90:93], v[68:71], v[32:47]
	s_waitcnt lgkmcnt(1)
	v_mfma_f32_32x32x16_bf16 v[16:31], v[94:97], v[68:71], v[16:31]
	s_waitcnt lgkmcnt(0)
	v_mfma_f32_32x32x16_bf16 v[0:15], v[98:101], v[68:71], v[0:15]
	s_nop 0
	ds_bpermute_b32 v65, v165, v64
	v_lshl_or_b32 v66, s39, 6, v252
	s_cmp_lg_u32 s40, 1
	v_mad_u32_u24 v67, v66, s31, 0
	s_waitcnt lgkmcnt(0)
	v_add_f32_e32 v201, v64, v65
	s_barrier
	s_cbranch_scc1 .LBB0_620
	ds_write2_b64 v67, v[48:49], v[50:51] offset1:1
	ds_write2_b64 v67, v[52:53], v[54:55] offset0:2 offset1:3
	ds_write2_b64 v67, v[56:57], v[58:59] offset0:4 offset1:5
	ds_write2_b64 v67, v[60:61], v[62:63] offset0:6 offset1:7
	ds_write2_b64 v67, v[32:33], v[34:35] offset0:8 offset1:9
	ds_write2_b64 v67, v[36:37], v[38:39] offset0:10 offset1:11
	ds_write2_b64 v67, v[40:41], v[42:43] offset0:12 offset1:13
	ds_write2_b64 v67, v[44:45], v[46:47] offset0:14 offset1:15
	ds_write2_b64 v67, v[16:17], v[18:19] offset0:16 offset1:17
	ds_write2_b64 v67, v[20:21], v[22:23] offset0:18 offset1:19
	ds_write2_b64 v67, v[24:25], v[26:27] offset0:20 offset1:21
	ds_write2_b64 v67, v[28:29], v[30:31] offset0:22 offset1:23
	ds_write2_b64 v67, v[0:1], v[2:3] offset0:24 offset1:25
	ds_write2_b64 v67, v[4:5], v[6:7] offset0:26 offset1:27
	ds_write2_b64 v67, v[8:9], v[10:11] offset0:28 offset1:29
	ds_write2_b64 v67, v[12:13], v[14:15] offset0:30 offset1:31
	ds_write_b64 v67, v[200:201] offset:256

; DI void xcd_barrier(const XcdBarrier& b) {
;     asm volatile("s_waitcnt vmcnt(0)" ::: "memory");
;     __syncthreads();
;     if (threadIdx.x == 0) {
.LBB0_625:
	s_setprio 0
	s_cmp_gt_i32 s85, 5
	s_cselect_b64 s[4:5], -1, 0
	s_and_b64 s[0:1], s[14:15], s[4:5]
	s_andn2_b64 vcc, exec, s[0:1]
	s_cbranch_vccnz .LBB0_679
	s_waitcnt vmcnt(0) lgkmcnt(0)
	s_barrier
	v_readlane_b32 s3, v254, 3
	s_nop 3
	s_cmp_lg_u32 s3, 1
	s_cbranch_scc1 .Lmb5_notw1
	buffer_inv sc1
	s_waitcnt vmcnt(0)
	s_branch .Lmb5_end
